# FFN-in GEMM: epilogues of the two wave halves un-aligned for all but the last tile (pre-epilogue wr==0 barrier only when no next tile, post-epilogue wr==1 barrier removed)
# baseline (speedup 1.0000x reference)
.LBB0_860:
	ds_read_b128 v[154:157], v133
	ds_read_b128 v[158:161], v133 offset:1024
	ds_read_b128 v[162:165], v133 offset:2048
	ds_read_b128 v[166:169], v133 offset:3072
	ds_read_b128 v[170:173], v150
	ds_read_b128 v[174:177], v150 offset:1024
	ds_read_b128 v[178:181], v150 offset:2048
	ds_read_b128 v[182:185], v150 offset:3072
	s_add_u32 s54, s52, 0xfffc0080
	s_addc_u32 s55, s53, -1
	s_cmp_eq_u32 s70, 12
	s_cselect_b32 s57, s25, s55
	s_cselect_b32 s56, s66, s54
	s_cselect_b32 s55, s23, s69
	s_cselect_b32 s54, s67, s68
	v_lshl_add_u64 v[218:219], s[52:53], 0, v[148:149]
	s_add_i32 m0, s33, 0xc000
	ds_read_b128 v[186:189], v151
	ds_read_b128 v[190:193], v151 offset:1024
	ds_read_b128 v[194:197], v151 offset:2048
	ds_read_b128 v[198:201], v151 offset:3072
	ds_read_b128 v[202:205], v151 offset:4096
	ds_read_b128 v[206:209], v151 offset:5120
	ds_read_b128 v[210:213], v151 offset:6144
	ds_read_b128 v[214:217], v151 offset:7168
	global_load_lds_dwordx4 v[218:219], off
	v_lshl_add_u64 v[218:219], s[52:53], 0, v[146:147]
	s_add_i32 m0, s33, 0xe000
	s_nop 0
	global_load_lds_dwordx4 v[218:219], off
	s_waitcnt vmcnt(8)
	s_waitcnt lgkmcnt(0)
	s_barrier
	s_setprio 1
	s_waitcnt lgkmcnt(0)
	v_mfma_f32_16x16x32_bf16 v[126:129], v[154:157], v[186:189], v[126:129]
	v_mfma_f32_16x16x32_bf16 v[118:121], v[162:165], v[186:189], v[118:121]
	v_mfma_f32_16x16x32_bf16 v[110:113], v[154:157], v[194:197], v[110:113]
	v_mfma_f32_16x16x32_bf16 v[102:105], v[162:165], v[194:197], v[102:105]
	v_mfma_f32_16x16x32_bf16 v[94:97], v[154:157], v[202:205], v[94:97]
	v_mfma_f32_16x16x32_bf16 v[86:89], v[162:165], v[202:205], v[86:89]
	v_mfma_f32_16x16x32_bf16 v[78:81], v[154:157], v[210:213], v[78:81]
	v_mfma_f32_16x16x32_bf16 v[70:73], v[162:165], v[210:213], v[70:73]
	v_mfma_f32_16x16x32_bf16 v[126:129], v[158:161], v[190:193], v[126:129]
	v_mfma_f32_16x16x32_bf16 v[118:121], v[166:169], v[190:193], v[118:121]
	v_mfma_f32_16x16x32_bf16 v[110:113], v[158:161], v[198:201], v[110:113]
	v_mfma_f32_16x16x32_bf16 v[102:105], v[166:169], v[198:201], v[102:105]
	v_mfma_f32_16x16x32_bf16 v[94:97], v[158:161], v[206:209], v[94:97]
	v_mfma_f32_16x16x32_bf16 v[86:89], v[166:169], v[206:209], v[86:89]
	v_mfma_f32_16x16x32_bf16 v[78:81], v[158:161], v[214:217], v[78:81]
	v_mfma_f32_16x16x32_bf16 v[70:73], v[166:169], v[214:217], v[70:73]
	s_setprio 0
	s_setprio 1
	v_mfma_f32_16x16x32_bf16 v[122:125], v[170:173], v[186:189], v[122:125]
	v_mfma_f32_16x16x32_bf16 v[114:117], v[178:181], v[186:189], v[114:117]
	v_mfma_f32_16x16x32_bf16 v[106:109], v[170:173], v[194:197], v[106:109]
	v_mfma_f32_16x16x32_bf16 v[98:101], v[178:181], v[194:197], v[98:101]
	v_mfma_f32_16x16x32_bf16 v[90:93], v[170:173], v[202:205], v[90:93]
	v_mfma_f32_16x16x32_bf16 v[82:85], v[178:181], v[202:205], v[82:85]
	v_mfma_f32_16x16x32_bf16 v[74:77], v[170:173], v[210:213], v[74:77]
	v_mfma_f32_16x16x32_bf16 v[66:69], v[178:181], v[210:213], v[66:69]
	v_mfma_f32_16x16x32_bf16 v[122:125], v[174:177], v[190:193], v[122:125]
	v_mfma_f32_16x16x32_bf16 v[114:117], v[182:185], v[190:193], v[114:117]
	v_mfma_f32_16x16x32_bf16 v[106:109], v[174:177], v[198:201], v[106:109]
	v_mfma_f32_16x16x32_bf16 v[98:101], v[182:185], v[198:201], v[98:101]
	v_mfma_f32_16x16x32_bf16 v[90:93], v[174:177], v[206:209], v[90:93]
	v_mfma_f32_16x16x32_bf16 v[82:85], v[182:185], v[206:209], v[82:85]
	v_mfma_f32_16x16x32_bf16 v[74:77], v[174:177], v[214:217], v[74:77]
	v_mfma_f32_16x16x32_bf16 v[66:69], v[182:185], v[214:217], v[66:69]
	s_setprio 0
	s_barrier
	s_mov_b32 m0, s28
	v_lshl_add_u64 v[218:219], s[54:55], 0, v[140:141]
	s_add_u32 s72, s54, 0x40000
	ds_read_b128 v[186:189], v151 offset:16384
	ds_read_b128 v[190:193], v151 offset:17408
	ds_read_b128 v[194:197], v151 offset:18432
	ds_read_b128 v[198:201], v151 offset:19456
	ds_read_b128 v[202:205], v151 offset:20480
	ds_read_b128 v[206:209], v151 offset:21504
	ds_read_b128 v[210:213], v151 offset:22528
	ds_read_b128 v[214:217], v151 offset:23552
	global_load_lds_dwordx4 v[218:219], off
	v_lshl_add_u64 v[220:221], s[54:55], 0, v[144:145]
	s_mov_b32 m0, s29
	s_addc_u32 s73, s55, 0
	global_load_lds_dwordx4 v[220:221], off
	v_lshl_add_u64 v[222:223], s[72:73], 0, v[140:141]
	s_mov_b32 m0, s30
	v_lshl_add_u64 v[224:225], s[56:57], 0, v[142:143]
	global_load_lds_dwordx4 v[222:223], off
	v_lshl_add_u64 v[222:223], s[72:73], 0, v[144:145]
	s_mov_b32 m0, s31
	s_nop 0
	global_load_lds_dwordx4 v[222:223], off
	v_lshl_add_u64 v[222:223], s[56:57], 0, v[138:139]
	s_mov_b32 m0, s33
	s_nop 0
	global_load_lds_dwordx4 v[222:223], off
	s_mov_b32 m0, s34
	s_nop 0
	global_load_lds_dwordx4 v[224:225], off
	s_waitcnt vmcnt(8)
	s_waitcnt lgkmcnt(0)
	s_barrier
	s_setprio 1
	s_waitcnt lgkmcnt(0)
	v_mfma_f32_16x16x32_bf16 v[62:65], v[154:157], v[186:189], v[62:65]
	v_mfma_f32_16x16x32_bf16 v[54:57], v[162:165], v[186:189], v[54:57]
	v_mfma_f32_16x16x32_bf16 v[46:49], v[154:157], v[194:197], v[46:49]
	v_mfma_f32_16x16x32_bf16 v[38:41], v[162:165], v[194:197], v[38:41]
	v_mfma_f32_16x16x32_bf16 v[30:33], v[154:157], v[202:205], v[30:33]
	v_mfma_f32_16x16x32_bf16 v[22:25], v[162:165], v[202:205], v[22:25]
	v_mfma_f32_16x16x32_bf16 v[14:17], v[154:157], v[210:213], v[14:17]
	v_mfma_f32_16x16x32_bf16 v[6:9], v[162:165], v[210:213], v[6:9]
	v_mfma_f32_16x16x32_bf16 v[62:65], v[158:161], v[190:193], v[62:65]
	v_mfma_f32_16x16x32_bf16 v[54:57], v[166:169], v[190:193], v[54:57]
	v_mfma_f32_16x16x32_bf16 v[46:49], v[158:161], v[198:201], v[46:49]
	v_mfma_f32_16x16x32_bf16 v[38:41], v[166:169], v[198:201], v[38:41]
	v_mfma_f32_16x16x32_bf16 v[30:33], v[158:161], v[206:209], v[30:33]
	v_mfma_f32_16x16x32_bf16 v[22:25], v[166:169], v[206:209], v[22:25]
	v_mfma_f32_16x16x32_bf16 v[14:17], v[158:161], v[214:217], v[14:17]
	v_mfma_f32_16x16x32_bf16 v[6:9], v[166:169], v[214:217], v[6:9]
	s_setprio 0
	s_setprio 1
	v_mfma_f32_16x16x32_bf16 v[58:61], v[170:173], v[186:189], v[58:61]
	v_mfma_f32_16x16x32_bf16 v[50:53], v[178:181], v[186:189], v[50:53]
	v_mfma_f32_16x16x32_bf16 v[42:45], v[170:173], v[194:197], v[42:45]
	v_mfma_f32_16x16x32_bf16 v[34:37], v[178:181], v[194:197], v[34:37]
	v_mfma_f32_16x16x32_bf16 v[26:29], v[170:173], v[202:205], v[26:29]
	v_mfma_f32_16x16x32_bf16 v[18:21], v[178:181], v[202:205], v[18:21]
	v_mfma_f32_16x16x32_bf16 v[10:13], v[170:173], v[210:213], v[10:13]
	v_mfma_f32_16x16x32_bf16 v[2:5], v[178:181], v[210:213], v[2:5]
	v_mfma_f32_16x16x32_bf16 v[58:61], v[174:177], v[190:193], v[58:61]
	v_mfma_f32_16x16x32_bf16 v[50:53], v[182:185], v[190:193], v[50:53]
	v_mfma_f32_16x16x32_bf16 v[42:45], v[174:177], v[198:201], v[42:45]
	v_mfma_f32_16x16x32_bf16 v[34:37], v[182:185], v[198:201], v[34:37]
	v_mfma_f32_16x16x32_bf16 v[26:29], v[174:177], v[206:209], v[26:29]
	v_mfma_f32_16x16x32_bf16 v[18:21], v[182:185], v[206:209], v[18:21]
	v_mfma_f32_16x16x32_bf16 v[10:13], v[174:177], v[214:217], v[10:13]
	v_mfma_f32_16x16x32_bf16 v[2:5], v[182:185], v[214:217], v[2:5]
	s_setprio 0
	s_barrier
	ds_read_b128 v[154:157], v152
	ds_read_b128 v[158:161], v152 offset:1024
	ds_read_b128 v[162:165], v152 offset:2048
	ds_read_b128 v[166:169], v152 offset:3072
	ds_read_b128 v[170:173], v153
	ds_read_b128 v[174:177], v153 offset:1024
	ds_read_b128 v[178:181], v153 offset:2048
	ds_read_b128 v[182:185], v153 offset:3072
	s_add_u32 s56, s56, 0x40000
	s_addc_u32 s57, s57, 0
	s_mov_b32 m0, s35
	v_lshl_add_u64 v[226:227], s[56:57], 0, v[138:139]
	ds_read_b128 v[186:189], v151 offset:32768
	ds_read_b128 v[190:193], v151 offset:33792
	ds_read_b128 v[194:197], v151 offset:34816
	ds_read_b128 v[198:201], v151 offset:35840
	ds_read_b128 v[202:205], v151 offset:36864
	ds_read_b128 v[206:209], v151 offset:37888
	ds_read_b128 v[210:213], v151 offset:38912
	ds_read_b128 v[214:217], v151 offset:39936
	global_load_lds_dwordx4 v[226:227], off
	v_lshl_add_u64 v[226:227], s[56:57], 0, v[142:143]
	s_mov_b32 m0, s36
	s_nop 0
	global_load_lds_dwordx4 v[226:227], off
	s_waitcnt vmcnt(8)
	s_waitcnt lgkmcnt(0)
	s_barrier
	s_setprio 1
	s_waitcnt lgkmcnt(0)
	v_mfma_f32_16x16x32_bf16 v[126:129], v[154:157], v[186:189], v[126:129]
	v_mfma_f32_16x16x32_bf16 v[118:121], v[162:165], v[186:189], v[118:121]
	v_mfma_f32_16x16x32_bf16 v[110:113], v[154:157], v[194:197], v[110:113]
	v_mfma_f32_16x16x32_bf16 v[102:105], v[162:165], v[194:197], v[102:105]
	v_mfma_f32_16x16x32_bf16 v[94:97], v[154:157], v[202:205], v[94:97]
	v_mfma_f32_16x16x32_bf16 v[86:89], v[162:165], v[202:205], v[86:89]
	v_mfma_f32_16x16x32_bf16 v[78:81], v[154:157], v[210:213], v[78:81]
	v_mfma_f32_16x16x32_bf16 v[70:73], v[162:165], v[210:213], v[70:73]
	v_mfma_f32_16x16x32_bf16 v[126:129], v[158:161], v[190:193], v[126:129]
	v_mfma_f32_16x16x32_bf16 v[118:121], v[166:169], v[190:193], v[118:121]
	v_mfma_f32_16x16x32_bf16 v[110:113], v[158:161], v[198:201], v[110:113]
	v_mfma_f32_16x16x32_bf16 v[102:105], v[166:169], v[198:201], v[102:105]
	v_mfma_f32_16x16x32_bf16 v[94:97], v[158:161], v[206:209], v[94:97]
	v_mfma_f32_16x16x32_bf16 v[86:89], v[166:169], v[206:209], v[86:89]
	v_mfma_f32_16x16x32_bf16 v[78:81], v[158:161], v[214:217], v[78:81]
	v_mfma_f32_16x16x32_bf16 v[70:73], v[166:169], v[214:217], v[70:73]
	s_setprio 0
	s_setprio 1
	v_mfma_f32_16x16x32_bf16 v[122:125], v[170:173], v[186:189], v[122:125]
	v_mfma_f32_16x16x32_bf16 v[114:117], v[178:181], v[186:189], v[114:117]
	v_mfma_f32_16x16x32_bf16 v[106:109], v[170:173], v[194:197], v[106:109]
	v_mfma_f32_16x16x32_bf16 v[98:101], v[178:181], v[194:197], v[98:101]
	v_mfma_f32_16x16x32_bf16 v[90:93], v[170:173], v[202:205], v[90:93]
	v_mfma_f32_16x16x32_bf16 v[82:85], v[178:181], v[202:205], v[82:85]
	v_mfma_f32_16x16x32_bf16 v[74:77], v[170:173], v[210:213], v[74:77]
	v_mfma_f32_16x16x32_bf16 v[66:69], v[178:181], v[210:213], v[66:69]
	v_mfma_f32_16x16x32_bf16 v[122:125], v[174:177], v[190:193], v[122:125]
	v_mfma_f32_16x16x32_bf16 v[114:117], v[182:185], v[190:193], v[114:117]
	v_mfma_f32_16x16x32_bf16 v[106:109], v[174:177], v[198:201], v[106:109]
	v_mfma_f32_16x16x32_bf16 v[98:101], v[182:185], v[198:201], v[98:101]
	v_mfma_f32_16x16x32_bf16 v[90:93], v[174:177], v[206:209], v[90:93]
	v_mfma_f32_16x16x32_bf16 v[82:85], v[182:185], v[206:209], v[82:85]
	v_mfma_f32_16x16x32_bf16 v[74:77], v[174:177], v[214:217], v[74:77]
	v_mfma_f32_16x16x32_bf16 v[66:69], v[182:185], v[214:217], v[66:69]
	s_setprio 0
	s_barrier
	s_mov_b32 m0, s51
	v_lshl_add_u64 v[218:219], v[218:219], 0, s[8:9]
	s_add_u32 s54, s54, 0x40080
	ds_read_b128 v[186:189], v151 offset:49152
	ds_read_b128 v[190:193], v151 offset:50176
	ds_read_b128 v[194:197], v151 offset:51200
	ds_read_b128 v[198:201], v151 offset:52224
	ds_read_b128 v[202:205], v151 offset:53248
	ds_read_b128 v[206:209], v151 offset:54272
	ds_read_b128 v[210:213], v151 offset:55296
	ds_read_b128 v[214:217], v151 offset:56320
	global_load_lds_dwordx4 v[218:219], off
	v_lshl_add_u64 v[218:219], v[220:221], 0, s[8:9]
	s_mov_b32 m0, s58
	s_addc_u32 s55, s55, 0
	global_load_lds_dwordx4 v[218:219], off
	v_lshl_add_u64 v[218:219], s[54:55], 0, v[140:141]
	s_mov_b32 m0, s61
	s_nop 0
	global_load_lds_dwordx4 v[218:219], off
	v_lshl_add_u64 v[218:219], s[54:55], 0, v[144:145]
	s_mov_b32 m0, s62
	s_nop 0
	global_load_lds_dwordx4 v[218:219], off
	v_lshl_add_u64 v[218:219], v[222:223], 0, s[8:9]
	s_mov_b32 m0, s59
	s_nop 0
	global_load_lds_dwordx4 v[218:219], off
	v_lshl_add_u64 v[218:219], v[224:225], 0, s[8:9]
	s_mov_b32 m0, s60
	s_nop 0
	global_load_lds_dwordx4 v[218:219], off
	s_waitcnt vmcnt(8)
	s_waitcnt lgkmcnt(0)
	s_barrier
	s_setprio 1
	s_waitcnt lgkmcnt(0)
	v_mfma_f32_16x16x32_bf16 v[62:65], v[154:157], v[186:189], v[62:65]
	v_mfma_f32_16x16x32_bf16 v[54:57], v[162:165], v[186:189], v[54:57]
	v_mfma_f32_16x16x32_bf16 v[46:49], v[154:157], v[194:197], v[46:49]
	v_mfma_f32_16x16x32_bf16 v[38:41], v[162:165], v[194:197], v[38:41]
	v_mfma_f32_16x16x32_bf16 v[30:33], v[154:157], v[202:205], v[30:33]
	v_mfma_f32_16x16x32_bf16 v[22:25], v[162:165], v[202:205], v[22:25]
	v_mfma_f32_16x16x32_bf16 v[14:17], v[154:157], v[210:213], v[14:17]
	v_mfma_f32_16x16x32_bf16 v[6:9], v[162:165], v[210:213], v[6:9]
	v_mfma_f32_16x16x32_bf16 v[62:65], v[158:161], v[190:193], v[62:65]
	v_mfma_f32_16x16x32_bf16 v[54:57], v[166:169], v[190:193], v[54:57]
	v_mfma_f32_16x16x32_bf16 v[46:49], v[158:161], v[198:201], v[46:49]
	v_mfma_f32_16x16x32_bf16 v[38:41], v[166:169], v[198:201], v[38:41]
	v_mfma_f32_16x16x32_bf16 v[30:33], v[158:161], v[206:209], v[30:33]
	v_mfma_f32_16x16x32_bf16 v[22:25], v[166:169], v[206:209], v[22:25]
	v_mfma_f32_16x16x32_bf16 v[14:17], v[158:161], v[214:217], v[14:17]
	v_mfma_f32_16x16x32_bf16 v[6:9], v[166:169], v[214:217], v[6:9]
	s_setprio 0
	s_setprio 1
	v_mfma_f32_16x16x32_bf16 v[58:61], v[170:173], v[186:189], v[58:61]
	v_mfma_f32_16x16x32_bf16 v[50:53], v[178:181], v[186:189], v[50:53]
	v_mfma_f32_16x16x32_bf16 v[42:45], v[170:173], v[194:197], v[42:45]
	v_mfma_f32_16x16x32_bf16 v[34:37], v[178:181], v[194:197], v[34:37]
	v_mfma_f32_16x16x32_bf16 v[26:29], v[170:173], v[202:205], v[26:29]
	v_mfma_f32_16x16x32_bf16 v[18:21], v[178:181], v[202:205], v[18:21]
	v_mfma_f32_16x16x32_bf16 v[10:13], v[170:173], v[210:213], v[10:13]
	v_mfma_f32_16x16x32_bf16 v[2:5], v[178:181], v[210:213], v[2:5]
	v_mfma_f32_16x16x32_bf16 v[58:61], v[174:177], v[190:193], v[58:61]
	v_mfma_f32_16x16x32_bf16 v[50:53], v[182:185], v[190:193], v[50:53]
	v_mfma_f32_16x16x32_bf16 v[42:45], v[174:177], v[198:201], v[42:45]
	v_mfma_f32_16x16x32_bf16 v[34:37], v[182:185], v[198:201], v[34:37]
	v_mfma_f32_16x16x32_bf16 v[26:29], v[174:177], v[206:209], v[26:29]
	v_mfma_f32_16x16x32_bf16 v[18:21], v[182:185], v[206:209], v[18:21]
	v_mfma_f32_16x16x32_bf16 v[10:13], v[174:177], v[214:217], v[10:13]
	v_mfma_f32_16x16x32_bf16 v[2:5], v[182:185], v[214:217], v[2:5]
	s_setprio 0
	s_barrier
	s_add_i32 s70, s70, 2
	s_add_u32 s68, s68, 0x100
	s_addc_u32 s69, s69, 0
	s_add_u32 s52, s52, 0x100
	s_addc_u32 s53, s53, 0
	s_cmp_gt_u32 s70, 13
	s_cbranch_scc0 .LBB0_860
	s_andn2_b64 vcc, s[10:11], s[46:47]
	s_and_b64 vcc, exec, vcc
	s_cbranch_vccz .LBB0_863
	s_barrier
.LBB0_863:
	s_mov_b32 s98, 0xbfb8aa3b
	s_mov_b32 s99, 0xbfb8aa3b
	v_lshl_or_b32 v156, s65, 7, v131
	v_lshl_add_u32 v154, s50, 8, v1
	v_pk_mul_f32 v[230:231], v[126:127], s[98:99]
	v_exp_f32_e32 v230, v230
	v_exp_f32_e32 v231, v231
	v_add_f32_e32 v230, 1.0, v230
	v_add_f32_e32 v231, 1.0, v231
	v_rcp_f32_e32 v230, v230
	v_rcp_f32_e32 v231, v231
	v_mul_f32_e32 v234, v126, v230
	v_mul_f32_e32 v235, v127, v231
	v_pk_mul_f32 v[234:235], v[234:235], v[122:123]
	v_cvt_pk_bf16_f32 v122, v234, v235
	v_pk_mul_f32 v[230:231], v[128:129], s[98:99]
	v_exp_f32_e32 v230, v230
	v_exp_f32_e32 v231, v231
	v_add_f32_e32 v230, 1.0, v230
	v_add_f32_e32 v231, 1.0, v231
	v_rcp_f32_e32 v230, v230
	v_rcp_f32_e32 v231, v231
	v_mul_f32_e32 v236, v128, v230
	v_mul_f32_e32 v237, v129, v231
	v_pk_mul_f32 v[236:237], v[236:237], v[124:125]
	v_cvt_pk_bf16_f32 v123, v236, v237
	v_pk_mul_f32 v[230:231], v[118:119], s[98:99]
	v_exp_f32_e32 v230, v230
	v_exp_f32_e32 v231, v231
	v_add_f32_e32 v230, 1.0, v230
	v_add_f32_e32 v231, 1.0, v231
	v_rcp_f32_e32 v230, v230
	v_rcp_f32_e32 v231, v231
	v_mul_f32_e32 v238, v118, v230
	v_mul_f32_e32 v239, v119, v231
	v_pk_mul_f32 v[238:239], v[238:239], v[114:115]
	v_cvt_pk_bf16_f32 v124, v238, v239
	v_pk_mul_f32 v[230:231], v[120:121], s[98:99]
	v_exp_f32_e32 v230, v230
	v_exp_f32_e32 v231, v231
	v_add_f32_e32 v230, 1.0, v230
	v_add_f32_e32 v231, 1.0, v231
	v_rcp_f32_e32 v230, v230
	v_rcp_f32_e32 v231, v231
	v_mul_f32_e32 v240, v120, v230
	v_mul_f32_e32 v241, v121, v231
	v_pk_mul_f32 v[240:241], v[240:241], v[116:117]
	v_cvt_pk_bf16_f32 v125, v240, v241
	v_ashrrev_i32_e32 v157, 31, v156
	v_mov_b64_e32 v[114:115], s[16:17]
	v_mad_i64_i32 v[118:119], s[52:53], v154, s64, v[114:115]
	v_lshlrev_b64 v[116:117], 1, v[156:157]
	v_lshl_add_u64 v[118:119], v[118:119], 0, v[116:117]
	global_store_dwordx4 v[118:119], v[122:125], off
	s_nop 1
	v_pk_mul_f32 v[230:231], v[110:111], s[98:99]
	v_exp_f32_e32 v230, v230
	v_exp_f32_e32 v231, v231
	v_add_f32_e32 v230, 1.0, v230
	v_add_f32_e32 v231, 1.0, v231
	v_rcp_f32_e32 v230, v230
	v_rcp_f32_e32 v231, v231
	v_mul_f32_e32 v234, v110, v230
	v_mul_f32_e32 v235, v111, v231
	v_pk_mul_f32 v[234:235], v[234:235], v[106:107]
	v_cvt_pk_bf16_f32 v106, v234, v235
	v_pk_mul_f32 v[230:231], v[112:113], s[98:99]
	v_exp_f32_e32 v230, v230
	v_exp_f32_e32 v231, v231
	v_add_f32_e32 v230, 1.0, v230
	v_add_f32_e32 v231, 1.0, v231
	v_rcp_f32_e32 v230, v230
	v_rcp_f32_e32 v231, v231
	v_mul_f32_e32 v236, v112, v230
	v_mul_f32_e32 v237, v113, v231
	v_pk_mul_f32 v[236:237], v[236:237], v[108:109]
	v_cvt_pk_bf16_f32 v107, v236, v237
	v_pk_mul_f32 v[230:231], v[102:103], s[98:99]
	v_exp_f32_e32 v230, v230
	v_exp_f32_e32 v231, v231
	v_add_f32_e32 v230, 1.0, v230
	v_add_f32_e32 v231, 1.0, v231
	v_rcp_f32_e32 v230, v230
	v_rcp_f32_e32 v231, v231
	v_mul_f32_e32 v238, v102, v230
	v_mul_f32_e32 v239, v103, v231
	v_pk_mul_f32 v[238:239], v[238:239], v[98:99]
	v_cvt_pk_bf16_f32 v108, v238, v239
	v_pk_mul_f32 v[230:231], v[104:105], s[98:99]
	v_exp_f32_e32 v230, v230
	v_exp_f32_e32 v231, v231
	v_add_f32_e32 v230, 1.0, v230
	v_add_f32_e32 v231, 1.0, v231
	v_rcp_f32_e32 v230, v230
	v_rcp_f32_e32 v231, v231
	v_mul_f32_e32 v240, v104, v230
	v_mul_f32_e32 v241, v105, v231
	v_pk_mul_f32 v[240:241], v[240:241], v[100:101]
	v_cvt_pk_bf16_f32 v109, v240, v241
	v_or_b32_e32 v98, 16, v154
	v_mad_i64_i32 v[98:99], s[52:53], v98, s64, v[114:115]
	v_lshl_add_u64 v[98:99], v[98:99], 0, v[116:117]
	global_store_dwordx4 v[98:99], v[106:109], off
	v_pk_mul_f32 v[230:231], v[94:95], s[98:99]
	v_exp_f32_e32 v230, v230
	v_exp_f32_e32 v231, v231
	v_add_f32_e32 v230, 1.0, v230
	v_add_f32_e32 v231, 1.0, v231
	v_rcp_f32_e32 v230, v230
	v_rcp_f32_e32 v231, v231
	v_mul_f32_e32 v234, v94, v230
	v_mul_f32_e32 v235, v95, v231
	v_pk_mul_f32 v[234:235], v[234:235], v[90:91]
	v_cvt_pk_bf16_f32 v90, v234, v235
	v_pk_mul_f32 v[230:231], v[96:97], s[98:99]
	v_exp_f32_e32 v230, v230
	v_exp_f32_e32 v231, v231
	v_add_f32_e32 v230, 1.0, v230
	v_add_f32_e32 v231, 1.0, v231
	v_rcp_f32_e32 v230, v230
	v_rcp_f32_e32 v231, v231
	v_mul_f32_e32 v236, v96, v230
	v_mul_f32_e32 v237, v97, v231
	v_pk_mul_f32 v[236:237], v[236:237], v[92:93]
	v_cvt_pk_bf16_f32 v91, v236, v237
	v_pk_mul_f32 v[230:231], v[86:87], s[98:99]
	v_exp_f32_e32 v230, v230
	v_exp_f32_e32 v231, v231
	v_add_f32_e32 v230, 1.0, v230
	v_add_f32_e32 v231, 1.0, v231
	v_rcp_f32_e32 v230, v230
	v_rcp_f32_e32 v231, v231
	v_mul_f32_e32 v238, v86, v230
	v_mul_f32_e32 v239, v87, v231
	v_pk_mul_f32 v[238:239], v[238:239], v[82:83]
	v_cvt_pk_bf16_f32 v92, v238, v239
	v_pk_mul_f32 v[230:231], v[88:89], s[98:99]
	v_exp_f32_e32 v230, v230
	v_exp_f32_e32 v231, v231
	v_add_f32_e32 v230, 1.0, v230
	v_add_f32_e32 v231, 1.0, v231
	v_rcp_f32_e32 v230, v230
	v_rcp_f32_e32 v231, v231
	v_mul_f32_e32 v240, v88, v230
	v_mul_f32_e32 v241, v89, v231
	v_pk_mul_f32 v[240:241], v[240:241], v[84:85]
	v_cvt_pk_bf16_f32 v93, v240, v241
	v_or_b32_e32 v82, 32, v154
	v_mad_i64_i32 v[82:83], s[52:53], v82, s64, v[114:115]
	v_lshl_add_u64 v[82:83], v[82:83], 0, v[116:117]
	global_store_dwordx4 v[82:83], v[90:93], off
	v_pk_mul_f32 v[230:231], v[78:79], s[98:99]
	v_exp_f32_e32 v230, v230
	v_exp_f32_e32 v231, v231
	v_add_f32_e32 v230, 1.0, v230
	v_add_f32_e32 v231, 1.0, v231
	v_rcp_f32_e32 v230, v230
	v_rcp_f32_e32 v231, v231
	v_mul_f32_e32 v234, v78, v230
	v_mul_f32_e32 v235, v79, v231
	v_pk_mul_f32 v[234:235], v[234:235], v[74:75]
	v_cvt_pk_bf16_f32 v74, v234, v235
	v_pk_mul_f32 v[230:231], v[80:81], s[98:99]
	v_exp_f32_e32 v230, v230
	v_exp_f32_e32 v231, v231
	v_add_f32_e32 v230, 1.0, v230
	v_add_f32_e32 v231, 1.0, v231
	v_rcp_f32_e32 v230, v230
	v_rcp_f32_e32 v231, v231
	v_mul_f32_e32 v236, v80, v230
	v_mul_f32_e32 v237, v81, v231
	v_pk_mul_f32 v[236:237], v[236:237], v[76:77]
	v_cvt_pk_bf16_f32 v75, v236, v237
	v_pk_mul_f32 v[230:231], v[70:71], s[98:99]
	v_exp_f32_e32 v230, v230
	v_exp_f32_e32 v231, v231
	v_add_f32_e32 v230, 1.0, v230
	v_add_f32_e32 v231, 1.0, v231
	v_rcp_f32_e32 v230, v230
	v_rcp_f32_e32 v231, v231
	v_mul_f32_e32 v238, v70, v230
	v_mul_f32_e32 v239, v71, v231
	v_pk_mul_f32 v[238:239], v[238:239], v[66:67]
	v_cvt_pk_bf16_f32 v76, v238, v239
	v_pk_mul_f32 v[230:231], v[72:73], s[98:99]
	v_exp_f32_e32 v230, v230
	v_exp_f32_e32 v231, v231
	v_add_f32_e32 v230, 1.0, v230
	v_add_f32_e32 v231, 1.0, v231
	v_rcp_f32_e32 v230, v230
	v_rcp_f32_e32 v231, v231
	v_mul_f32_e32 v240, v72, v230
	v_mul_f32_e32 v241, v73, v231
	v_pk_mul_f32 v[240:241], v[240:241], v[68:69]
	v_cvt_pk_bf16_f32 v77, v240, v241
	v_or_b32_e32 v66, 48, v154
	v_mad_i64_i32 v[66:67], s[52:53], v66, s64, v[114:115]
	v_lshl_add_u64 v[66:67], v[66:67], 0, v[116:117]
	global_store_dwordx4 v[66:67], v[74:77], off
	v_pk_mul_f32 v[230:231], v[62:63], s[98:99]
	v_exp_f32_e32 v230, v230
	v_exp_f32_e32 v231, v231
	v_add_f32_e32 v230, 1.0, v230
	v_add_f32_e32 v231, 1.0, v231
	v_rcp_f32_e32 v230, v230
	v_rcp_f32_e32 v231, v231
	v_mul_f32_e32 v234, v62, v230
	v_mul_f32_e32 v235, v63, v231
	v_pk_mul_f32 v[234:235], v[234:235], v[58:59]
	v_cvt_pk_bf16_f32 v58, v234, v235
	v_pk_mul_f32 v[230:231], v[64:65], s[98:99]
	v_exp_f32_e32 v230, v230
	v_exp_f32_e32 v231, v231
	v_add_f32_e32 v230, 1.0, v230
	v_add_f32_e32 v231, 1.0, v231
	v_rcp_f32_e32 v230, v230
	v_rcp_f32_e32 v231, v231
	v_mul_f32_e32 v236, v64, v230
	v_mul_f32_e32 v237, v65, v231
	v_pk_mul_f32 v[236:237], v[236:237], v[60:61]
	v_cvt_pk_bf16_f32 v59, v236, v237
	v_pk_mul_f32 v[230:231], v[54:55], s[98:99]
	v_exp_f32_e32 v230, v230
	v_exp_f32_e32 v231, v231
	v_add_f32_e32 v230, 1.0, v230
	v_add_f32_e32 v231, 1.0, v231
	v_rcp_f32_e32 v230, v230
	v_rcp_f32_e32 v231, v231
	v_mul_f32_e32 v238, v54, v230
	v_mul_f32_e32 v239, v55, v231
	v_pk_mul_f32 v[238:239], v[238:239], v[50:51]
	v_cvt_pk_bf16_f32 v60, v238, v239
	v_pk_mul_f32 v[230:231], v[56:57], s[98:99]
	v_exp_f32_e32 v230, v230
	v_exp_f32_e32 v231, v231
	v_add_f32_e32 v230, 1.0, v230
	v_add_f32_e32 v231, 1.0, v231
	v_rcp_f32_e32 v230, v230
	v_rcp_f32_e32 v231, v231
	v_mul_f32_e32 v240, v56, v230
	v_mul_f32_e32 v241, v57, v231
	v_pk_mul_f32 v[240:241], v[240:241], v[52:53]
	v_add_u32_e32 v66, 0x80, v154
	v_cvt_pk_bf16_f32 v61, v240, v241
	v_mad_i64_i32 v[50:51], s[52:53], v66, s64, v[114:115]
	v_lshl_add_u64 v[50:51], v[50:51], 0, v[116:117]
	global_store_dwordx4 v[50:51], v[58:61], off
	v_pk_mul_f32 v[230:231], v[46:47], s[98:99]
	v_exp_f32_e32 v230, v230
	v_exp_f32_e32 v231, v231
	v_add_f32_e32 v230, 1.0, v230
	v_add_f32_e32 v231, 1.0, v231
	v_rcp_f32_e32 v230, v230
	v_rcp_f32_e32 v231, v231
	v_mul_f32_e32 v234, v46, v230
	v_mul_f32_e32 v235, v47, v231
	v_pk_mul_f32 v[234:235], v[234:235], v[42:43]
	v_cvt_pk_bf16_f32 v42, v234, v235
	v_pk_mul_f32 v[230:231], v[48:49], s[98:99]
	v_exp_f32_e32 v230, v230
	v_exp_f32_e32 v231, v231
	v_add_f32_e32 v230, 1.0, v230
	v_add_f32_e32 v231, 1.0, v231
	v_rcp_f32_e32 v230, v230
	v_rcp_f32_e32 v231, v231
	v_mul_f32_e32 v236, v48, v230
	v_mul_f32_e32 v237, v49, v231
	v_pk_mul_f32 v[236:237], v[236:237], v[44:45]
	v_cvt_pk_bf16_f32 v43, v236, v237
	v_pk_mul_f32 v[230:231], v[38:39], s[98:99]
	v_exp_f32_e32 v230, v230
	v_exp_f32_e32 v231, v231
	v_add_f32_e32 v230, 1.0, v230
	v_add_f32_e32 v231, 1.0, v231
	v_rcp_f32_e32 v230, v230
	v_rcp_f32_e32 v231, v231
	v_mul_f32_e32 v238, v38, v230
	v_mul_f32_e32 v239, v39, v231
	v_pk_mul_f32 v[238:239], v[238:239], v[34:35]
	v_cvt_pk_bf16_f32 v44, v238, v239
	v_pk_mul_f32 v[230:231], v[40:41], s[98:99]
	v_exp_f32_e32 v230, v230
	v_exp_f32_e32 v231, v231
	v_add_f32_e32 v230, 1.0, v230
	v_add_f32_e32 v231, 1.0, v231
	v_rcp_f32_e32 v230, v230
	v_rcp_f32_e32 v231, v231
	v_mul_f32_e32 v240, v40, v230
	v_mul_f32_e32 v241, v41, v231
	v_pk_mul_f32 v[240:241], v[240:241], v[36:37]
	v_cvt_pk_bf16_f32 v45, v240, v241
	v_add_u32_e32 v34, 0x90, v154
	v_mad_i64_i32 v[34:35], s[52:53], v34, s64, v[114:115]
	v_lshl_add_u64 v[34:35], v[34:35], 0, v[116:117]
	global_store_dwordx4 v[34:35], v[42:45], off
	v_pk_mul_f32 v[230:231], v[30:31], s[98:99]
	v_exp_f32_e32 v230, v230
	v_exp_f32_e32 v231, v231
	v_add_f32_e32 v230, 1.0, v230
	v_add_f32_e32 v231, 1.0, v231
	v_rcp_f32_e32 v230, v230
	v_rcp_f32_e32 v231, v231
	v_mul_f32_e32 v234, v30, v230
	v_mul_f32_e32 v235, v31, v231
	v_pk_mul_f32 v[234:235], v[234:235], v[26:27]
	v_cvt_pk_bf16_f32 v26, v234, v235
	v_pk_mul_f32 v[230:231], v[32:33], s[98:99]
	v_exp_f32_e32 v230, v230
	v_exp_f32_e32 v231, v231
	v_add_f32_e32 v230, 1.0, v230
	v_add_f32_e32 v231, 1.0, v231
	v_rcp_f32_e32 v230, v230
	v_rcp_f32_e32 v231, v231
	v_mul_f32_e32 v236, v32, v230
	v_mul_f32_e32 v237, v33, v231
	v_pk_mul_f32 v[236:237], v[236:237], v[28:29]
	v_cvt_pk_bf16_f32 v27, v236, v237
	v_pk_mul_f32 v[230:231], v[22:23], s[98:99]
	v_exp_f32_e32 v230, v230
	v_exp_f32_e32 v231, v231
	v_add_f32_e32 v230, 1.0, v230
	v_add_f32_e32 v231, 1.0, v231
	v_rcp_f32_e32 v230, v230
	v_rcp_f32_e32 v231, v231
	v_mul_f32_e32 v238, v22, v230
	v_mul_f32_e32 v239, v23, v231
	v_pk_mul_f32 v[238:239], v[238:239], v[18:19]
	v_cvt_pk_bf16_f32 v28, v238, v239
	v_pk_mul_f32 v[230:231], v[24:25], s[98:99]
	v_exp_f32_e32 v230, v230
	v_exp_f32_e32 v231, v231
	v_add_f32_e32 v230, 1.0, v230
	v_add_f32_e32 v231, 1.0, v231
	v_rcp_f32_e32 v230, v230
	v_rcp_f32_e32 v231, v231
	v_mul_f32_e32 v240, v24, v230
	v_mul_f32_e32 v241, v25, v231
	v_pk_mul_f32 v[240:241], v[240:241], v[20:21]
	v_cvt_pk_bf16_f32 v29, v240, v241
	v_add_u32_e32 v18, 0xa0, v154
	v_mad_i64_i32 v[18:19], s[52:53], v18, s64, v[114:115]
	v_lshl_add_u64 v[18:19], v[18:19], 0, v[116:117]
	global_store_dwordx4 v[18:19], v[26:29], off
	v_pk_mul_f32 v[230:231], v[14:15], s[98:99]
	v_exp_f32_e32 v230, v230
	v_exp_f32_e32 v231, v231
	v_add_f32_e32 v230, 1.0, v230
	v_add_f32_e32 v231, 1.0, v231
	v_rcp_f32_e32 v230, v230
	v_rcp_f32_e32 v231, v231
	v_mul_f32_e32 v234, v14, v230
	v_mul_f32_e32 v235, v15, v231
	v_pk_mul_f32 v[234:235], v[234:235], v[10:11]
	v_cvt_pk_bf16_f32 v10, v234, v235
	v_pk_mul_f32 v[230:231], v[16:17], s[98:99]
	v_exp_f32_e32 v230, v230
	v_exp_f32_e32 v231, v231
	v_add_f32_e32 v230, 1.0, v230
	v_add_f32_e32 v231, 1.0, v231
	v_rcp_f32_e32 v230, v230
	v_rcp_f32_e32 v231, v231
	v_mul_f32_e32 v236, v16, v230
	v_mul_f32_e32 v237, v17, v231
	v_pk_mul_f32 v[236:237], v[236:237], v[12:13]
	v_cvt_pk_bf16_f32 v11, v236, v237
	v_pk_mul_f32 v[230:231], v[6:7], s[98:99]
	v_exp_f32_e32 v230, v230
	v_exp_f32_e32 v231, v231
	v_add_f32_e32 v230, 1.0, v230
	v_add_f32_e32 v231, 1.0, v231
	v_rcp_f32_e32 v230, v230
	v_rcp_f32_e32 v231, v231
	v_mul_f32_e32 v238, v6, v230
	v_mul_f32_e32 v239, v7, v231
	v_pk_mul_f32 v[238:239], v[238:239], v[2:3]
	v_cvt_pk_bf16_f32 v12, v238, v239
	v_pk_mul_f32 v[230:231], v[8:9], s[98:99]
	v_exp_f32_e32 v230, v230
	v_exp_f32_e32 v231, v231
	v_add_f32_e32 v230, 1.0, v230
	v_add_f32_e32 v231, 1.0, v231
	v_rcp_f32_e32 v230, v230
	v_rcp_f32_e32 v231, v231
	v_mul_f32_e32 v240, v8, v230
	v_mul_f32_e32 v241, v9, v231
	v_pk_mul_f32 v[240:241], v[240:241], v[4:5]
	v_cvt_pk_bf16_f32 v13, v240, v241
	v_add_u32_e32 v2, 0xb0, v154
	v_mad_i64_i32 v[2:3], s[52:53], v2, s64, v[114:115]
	v_lshl_add_u64 v[2:3], v[2:3], 0, v[116:117]
	s_andn2_b64 vcc, exec, s[46:47]
	s_mov_b64 s[46:47], -1
	global_store_dwordx4 v[2:3], v[10:13], off
	s_cbranch_vccnz .LBB0_852
	s_andn2_b64 vcc, exec, s[6:7]
	s_cbranch_vccnz .LBB0_851
	s_nop 0
	s_branch .LBB0_851

.LBB0_3212:
	ds_read_b128 v[148:151], v143
	ds_read_b128 v[152:155], v143 offset:1024
	ds_read_b128 v[156:159], v143 offset:2048
	ds_read_b128 v[160:163], v143 offset:3072
	ds_read_b128 v[164:167], v144
	ds_read_b128 v[168:171], v144 offset:1024
	ds_read_b128 v[172:175], v144 offset:2048
	ds_read_b128 v[176:179], v144 offset:3072
	s_add_u32 s52, s50, 0xfffc0080
	s_addc_u32 s53, s51, -1
	s_cmp_eq_u32 s69, 12
	s_cselect_b32 s55, s41, s53
	s_cselect_b32 s54, s65, s52
	s_cselect_b32 s53, s39, s68
	s_cselect_b32 s52, s66, s67
	v_lshl_add_u64 v[212:213], s[50:51], 0, v[140:141]
	s_add_i32 m0, s34, 0xc000
	ds_read_b128 v[180:183], v145
	ds_read_b128 v[184:187], v145 offset:1024
	ds_read_b128 v[188:191], v145 offset:2048
	ds_read_b128 v[192:195], v145 offset:3072
	ds_read_b128 v[196:199], v145 offset:4096
	ds_read_b128 v[200:203], v145 offset:5120
	ds_read_b128 v[204:207], v145 offset:6144
	ds_read_b128 v[208:211], v145 offset:7168
	global_load_lds_dwordx4 v[212:213], off
	v_lshl_add_u64 v[212:213], s[50:51], 0, v[138:139]
	s_add_i32 m0, s34, 0xe000
	s_nop 0
	global_load_lds_dwordx4 v[212:213], off
	s_waitcnt vmcnt(8)
	s_waitcnt lgkmcnt(0)
	s_barrier
	s_setprio 1
	s_waitcnt lgkmcnt(0)
	v_mfma_f32_16x16x32_bf16 v[126:129], v[148:151], v[180:183], v[126:129]
	v_mfma_f32_16x16x32_bf16 v[118:121], v[156:159], v[180:183], v[118:121]
	v_mfma_f32_16x16x32_bf16 v[110:113], v[148:151], v[188:191], v[110:113]
	v_mfma_f32_16x16x32_bf16 v[102:105], v[156:159], v[188:191], v[102:105]
	v_mfma_f32_16x16x32_bf16 v[94:97], v[148:151], v[196:199], v[94:97]
	v_mfma_f32_16x16x32_bf16 v[86:89], v[156:159], v[196:199], v[86:89]
	v_mfma_f32_16x16x32_bf16 v[78:81], v[148:151], v[204:207], v[78:81]
	v_mfma_f32_16x16x32_bf16 v[70:73], v[156:159], v[204:207], v[70:73]
	v_mfma_f32_16x16x32_bf16 v[126:129], v[152:155], v[184:187], v[126:129]
	v_mfma_f32_16x16x32_bf16 v[118:121], v[160:163], v[184:187], v[118:121]
	v_mfma_f32_16x16x32_bf16 v[110:113], v[152:155], v[192:195], v[110:113]
	v_mfma_f32_16x16x32_bf16 v[102:105], v[160:163], v[192:195], v[102:105]
	v_mfma_f32_16x16x32_bf16 v[94:97], v[152:155], v[200:203], v[94:97]
	v_mfma_f32_16x16x32_bf16 v[86:89], v[160:163], v[200:203], v[86:89]
	v_mfma_f32_16x16x32_bf16 v[78:81], v[152:155], v[208:211], v[78:81]
	v_mfma_f32_16x16x32_bf16 v[70:73], v[160:163], v[208:211], v[70:73]
	s_setprio 0
	s_setprio 1
	v_mfma_f32_16x16x32_bf16 v[122:125], v[164:167], v[180:183], v[122:125]
	v_mfma_f32_16x16x32_bf16 v[114:117], v[172:175], v[180:183], v[114:117]
	v_mfma_f32_16x16x32_bf16 v[106:109], v[164:167], v[188:191], v[106:109]
	v_mfma_f32_16x16x32_bf16 v[98:101], v[172:175], v[188:191], v[98:101]
	v_mfma_f32_16x16x32_bf16 v[90:93], v[164:167], v[196:199], v[90:93]
	v_mfma_f32_16x16x32_bf16 v[82:85], v[172:175], v[196:199], v[82:85]
	v_mfma_f32_16x16x32_bf16 v[74:77], v[164:167], v[204:207], v[74:77]
	v_mfma_f32_16x16x32_bf16 v[66:69], v[172:175], v[204:207], v[66:69]
	v_mfma_f32_16x16x32_bf16 v[122:125], v[168:171], v[184:187], v[122:125]
	v_mfma_f32_16x16x32_bf16 v[114:117], v[176:179], v[184:187], v[114:117]
	v_mfma_f32_16x16x32_bf16 v[106:109], v[168:171], v[192:195], v[106:109]
	v_mfma_f32_16x16x32_bf16 v[98:101], v[176:179], v[192:195], v[98:101]
	v_mfma_f32_16x16x32_bf16 v[90:93], v[168:171], v[200:203], v[90:93]
	v_mfma_f32_16x16x32_bf16 v[82:85], v[176:179], v[200:203], v[82:85]
	v_mfma_f32_16x16x32_bf16 v[74:77], v[168:171], v[208:211], v[74:77]
	v_mfma_f32_16x16x32_bf16 v[66:69], v[176:179], v[208:211], v[66:69]
	s_setprio 0
	s_barrier
	s_mov_b32 m0, s29
	v_lshl_add_u64 v[212:213], s[52:53], 0, v[132:133]
	s_add_u32 s70, s52, 0x40000
	ds_read_b128 v[180:183], v145 offset:16384
	ds_read_b128 v[184:187], v145 offset:17408
	ds_read_b128 v[188:191], v145 offset:18432
	ds_read_b128 v[192:195], v145 offset:19456
	ds_read_b128 v[196:199], v145 offset:20480
	ds_read_b128 v[200:203], v145 offset:21504
	ds_read_b128 v[204:207], v145 offset:22528
	ds_read_b128 v[208:211], v145 offset:23552
	global_load_lds_dwordx4 v[212:213], off
	v_lshl_add_u64 v[214:215], s[52:53], 0, v[136:137]
	s_mov_b32 m0, s30
	s_addc_u32 s71, s53, 0
	global_load_lds_dwordx4 v[214:215], off
	v_lshl_add_u64 v[216:217], s[70:71], 0, v[132:133]
	s_mov_b32 m0, s31
	v_lshl_add_u64 v[218:219], s[54:55], 0, v[134:135]
	global_load_lds_dwordx4 v[216:217], off
	v_lshl_add_u64 v[216:217], s[70:71], 0, v[136:137]
	s_mov_b32 m0, s33
	s_nop 0
	global_load_lds_dwordx4 v[216:217], off
	v_lshl_add_u64 v[216:217], s[54:55], 0, v[130:131]
	s_mov_b32 m0, s34
	s_nop 0
	global_load_lds_dwordx4 v[216:217], off
	s_mov_b32 m0, s35
	s_nop 0
	global_load_lds_dwordx4 v[218:219], off
	s_waitcnt vmcnt(8)
	s_waitcnt lgkmcnt(0)
	s_barrier
	s_setprio 1
	s_waitcnt lgkmcnt(0)
	v_mfma_f32_16x16x32_bf16 v[62:65], v[148:151], v[180:183], v[62:65]
	v_mfma_f32_16x16x32_bf16 v[54:57], v[156:159], v[180:183], v[54:57]
	v_mfma_f32_16x16x32_bf16 v[46:49], v[148:151], v[188:191], v[46:49]
	v_mfma_f32_16x16x32_bf16 v[38:41], v[156:159], v[188:191], v[38:41]
	v_mfma_f32_16x16x32_bf16 v[30:33], v[148:151], v[196:199], v[30:33]
	v_mfma_f32_16x16x32_bf16 v[22:25], v[156:159], v[196:199], v[22:25]
	v_mfma_f32_16x16x32_bf16 v[14:17], v[148:151], v[204:207], v[14:17]
	v_mfma_f32_16x16x32_bf16 v[6:9], v[156:159], v[204:207], v[6:9]
	v_mfma_f32_16x16x32_bf16 v[62:65], v[152:155], v[184:187], v[62:65]
	v_mfma_f32_16x16x32_bf16 v[54:57], v[160:163], v[184:187], v[54:57]
	v_mfma_f32_16x16x32_bf16 v[46:49], v[152:155], v[192:195], v[46:49]
	v_mfma_f32_16x16x32_bf16 v[38:41], v[160:163], v[192:195], v[38:41]
	v_mfma_f32_16x16x32_bf16 v[30:33], v[152:155], v[200:203], v[30:33]
	v_mfma_f32_16x16x32_bf16 v[22:25], v[160:163], v[200:203], v[22:25]
	v_mfma_f32_16x16x32_bf16 v[14:17], v[152:155], v[208:211], v[14:17]
	v_mfma_f32_16x16x32_bf16 v[6:9], v[160:163], v[208:211], v[6:9]
	s_setprio 0
	s_setprio 1
	v_mfma_f32_16x16x32_bf16 v[58:61], v[164:167], v[180:183], v[58:61]
	v_mfma_f32_16x16x32_bf16 v[50:53], v[172:175], v[180:183], v[50:53]
	v_mfma_f32_16x16x32_bf16 v[42:45], v[164:167], v[188:191], v[42:45]
	v_mfma_f32_16x16x32_bf16 v[34:37], v[172:175], v[188:191], v[34:37]
	v_mfma_f32_16x16x32_bf16 v[26:29], v[164:167], v[196:199], v[26:29]
	v_mfma_f32_16x16x32_bf16 v[18:21], v[172:175], v[196:199], v[18:21]
	v_mfma_f32_16x16x32_bf16 v[10:13], v[164:167], v[204:207], v[10:13]
	v_mfma_f32_16x16x32_bf16 v[2:5], v[172:175], v[204:207], v[2:5]
	v_mfma_f32_16x16x32_bf16 v[58:61], v[168:171], v[184:187], v[58:61]
	v_mfma_f32_16x16x32_bf16 v[50:53], v[176:179], v[184:187], v[50:53]
	v_mfma_f32_16x16x32_bf16 v[42:45], v[168:171], v[192:195], v[42:45]
	v_mfma_f32_16x16x32_bf16 v[34:37], v[176:179], v[192:195], v[34:37]
	v_mfma_f32_16x16x32_bf16 v[26:29], v[168:171], v[200:203], v[26:29]
	v_mfma_f32_16x16x32_bf16 v[18:21], v[176:179], v[200:203], v[18:21]
	v_mfma_f32_16x16x32_bf16 v[10:13], v[168:171], v[208:211], v[10:13]
	v_mfma_f32_16x16x32_bf16 v[2:5], v[176:179], v[208:211], v[2:5]
	s_setprio 0
	s_barrier
	ds_read_b128 v[148:151], v146
	ds_read_b128 v[152:155], v146 offset:1024
	ds_read_b128 v[156:159], v146 offset:2048
	ds_read_b128 v[160:163], v146 offset:3072
	ds_read_b128 v[164:167], v147
	ds_read_b128 v[168:171], v147 offset:1024
	ds_read_b128 v[172:175], v147 offset:2048
	ds_read_b128 v[176:179], v147 offset:3072
	s_add_u32 s54, s54, 0x40000
	s_addc_u32 s55, s55, 0
	s_mov_b32 m0, s36
	v_lshl_add_u64 v[220:221], s[54:55], 0, v[130:131]
	ds_read_b128 v[180:183], v145 offset:32768
	ds_read_b128 v[184:187], v145 offset:33792
	ds_read_b128 v[188:191], v145 offset:34816
	ds_read_b128 v[192:195], v145 offset:35840
	ds_read_b128 v[196:199], v145 offset:36864
	ds_read_b128 v[200:203], v145 offset:37888
	ds_read_b128 v[204:207], v145 offset:38912
	ds_read_b128 v[208:211], v145 offset:39936
	global_load_lds_dwordx4 v[220:221], off
	v_lshl_add_u64 v[220:221], s[54:55], 0, v[134:135]
	s_mov_b32 m0, s37
	s_nop 0
	global_load_lds_dwordx4 v[220:221], off
	s_waitcnt vmcnt(8)
	s_waitcnt lgkmcnt(0)
	s_barrier
	s_setprio 1
	s_waitcnt lgkmcnt(0)
	v_mfma_f32_16x16x32_bf16 v[126:129], v[148:151], v[180:183], v[126:129]
	v_mfma_f32_16x16x32_bf16 v[118:121], v[156:159], v[180:183], v[118:121]
	v_mfma_f32_16x16x32_bf16 v[110:113], v[148:151], v[188:191], v[110:113]
	v_mfma_f32_16x16x32_bf16 v[102:105], v[156:159], v[188:191], v[102:105]
	v_mfma_f32_16x16x32_bf16 v[94:97], v[148:151], v[196:199], v[94:97]
	v_mfma_f32_16x16x32_bf16 v[86:89], v[156:159], v[196:199], v[86:89]
	v_mfma_f32_16x16x32_bf16 v[78:81], v[148:151], v[204:207], v[78:81]
	v_mfma_f32_16x16x32_bf16 v[70:73], v[156:159], v[204:207], v[70:73]
	v_mfma_f32_16x16x32_bf16 v[126:129], v[152:155], v[184:187], v[126:129]
	v_mfma_f32_16x16x32_bf16 v[118:121], v[160:163], v[184:187], v[118:121]
	v_mfma_f32_16x16x32_bf16 v[110:113], v[152:155], v[192:195], v[110:113]
	v_mfma_f32_16x16x32_bf16 v[102:105], v[160:163], v[192:195], v[102:105]
	v_mfma_f32_16x16x32_bf16 v[94:97], v[152:155], v[200:203], v[94:97]
	v_mfma_f32_16x16x32_bf16 v[86:89], v[160:163], v[200:203], v[86:89]
	v_mfma_f32_16x16x32_bf16 v[78:81], v[152:155], v[208:211], v[78:81]
	v_mfma_f32_16x16x32_bf16 v[70:73], v[160:163], v[208:211], v[70:73]
	s_setprio 0
	s_setprio 1
	v_mfma_f32_16x16x32_bf16 v[122:125], v[164:167], v[180:183], v[122:125]
	v_mfma_f32_16x16x32_bf16 v[114:117], v[172:175], v[180:183], v[114:117]
	v_mfma_f32_16x16x32_bf16 v[106:109], v[164:167], v[188:191], v[106:109]
	v_mfma_f32_16x16x32_bf16 v[98:101], v[172:175], v[188:191], v[98:101]
	v_mfma_f32_16x16x32_bf16 v[90:93], v[164:167], v[196:199], v[90:93]
	v_mfma_f32_16x16x32_bf16 v[82:85], v[172:175], v[196:199], v[82:85]
	v_mfma_f32_16x16x32_bf16 v[74:77], v[164:167], v[204:207], v[74:77]
	v_mfma_f32_16x16x32_bf16 v[66:69], v[172:175], v[204:207], v[66:69]
	v_mfma_f32_16x16x32_bf16 v[122:125], v[168:171], v[184:187], v[122:125]
	v_mfma_f32_16x16x32_bf16 v[114:117], v[176:179], v[184:187], v[114:117]
	v_mfma_f32_16x16x32_bf16 v[106:109], v[168:171], v[192:195], v[106:109]
	v_mfma_f32_16x16x32_bf16 v[98:101], v[176:179], v[192:195], v[98:101]
	v_mfma_f32_16x16x32_bf16 v[90:93], v[168:171], v[200:203], v[90:93]
	v_mfma_f32_16x16x32_bf16 v[82:85], v[176:179], v[200:203], v[82:85]
	v_mfma_f32_16x16x32_bf16 v[74:77], v[168:171], v[208:211], v[74:77]
	v_mfma_f32_16x16x32_bf16 v[66:69], v[176:179], v[208:211], v[66:69]
	s_setprio 0
	s_barrier
	s_mov_b32 m0, s57
	v_lshl_add_u64 v[212:213], v[212:213], 0, s[8:9]
	s_add_u32 s52, s52, 0x40080
	ds_read_b128 v[180:183], v145 offset:49152
	ds_read_b128 v[184:187], v145 offset:50176
	ds_read_b128 v[188:191], v145 offset:51200
	ds_read_b128 v[192:195], v145 offset:52224
	ds_read_b128 v[196:199], v145 offset:53248
	ds_read_b128 v[200:203], v145 offset:54272
	ds_read_b128 v[204:207], v145 offset:55296
	ds_read_b128 v[208:211], v145 offset:56320
	global_load_lds_dwordx4 v[212:213], off
	v_lshl_add_u64 v[212:213], v[214:215], 0, s[8:9]
	s_mov_b32 m0, s58
	s_addc_u32 s53, s53, 0
	global_load_lds_dwordx4 v[212:213], off
	v_lshl_add_u64 v[212:213], s[52:53], 0, v[132:133]
	s_mov_b32 m0, s61
	s_nop 0
	global_load_lds_dwordx4 v[212:213], off
	v_lshl_add_u64 v[212:213], s[52:53], 0, v[136:137]
	s_mov_b32 m0, s62
	s_nop 0
	global_load_lds_dwordx4 v[212:213], off
	v_lshl_add_u64 v[212:213], v[216:217], 0, s[8:9]
	s_mov_b32 m0, s59
	s_nop 0
	global_load_lds_dwordx4 v[212:213], off
	v_lshl_add_u64 v[212:213], v[218:219], 0, s[8:9]
	s_mov_b32 m0, s60
	s_nop 0
	global_load_lds_dwordx4 v[212:213], off
	s_waitcnt vmcnt(8)
	s_waitcnt lgkmcnt(0)
	s_barrier
	s_setprio 1
	s_waitcnt lgkmcnt(0)
	v_mfma_f32_16x16x32_bf16 v[62:65], v[148:151], v[180:183], v[62:65]
	v_mfma_f32_16x16x32_bf16 v[54:57], v[156:159], v[180:183], v[54:57]
	v_mfma_f32_16x16x32_bf16 v[46:49], v[148:151], v[188:191], v[46:49]
	v_mfma_f32_16x16x32_bf16 v[38:41], v[156:159], v[188:191], v[38:41]
	v_mfma_f32_16x16x32_bf16 v[30:33], v[148:151], v[196:199], v[30:33]
	v_mfma_f32_16x16x32_bf16 v[22:25], v[156:159], v[196:199], v[22:25]
	v_mfma_f32_16x16x32_bf16 v[14:17], v[148:151], v[204:207], v[14:17]
	v_mfma_f32_16x16x32_bf16 v[6:9], v[156:159], v[204:207], v[6:9]
	v_mfma_f32_16x16x32_bf16 v[62:65], v[152:155], v[184:187], v[62:65]
	v_mfma_f32_16x16x32_bf16 v[54:57], v[160:163], v[184:187], v[54:57]
	v_mfma_f32_16x16x32_bf16 v[46:49], v[152:155], v[192:195], v[46:49]
	v_mfma_f32_16x16x32_bf16 v[38:41], v[160:163], v[192:195], v[38:41]
	v_mfma_f32_16x16x32_bf16 v[30:33], v[152:155], v[200:203], v[30:33]
	v_mfma_f32_16x16x32_bf16 v[22:25], v[160:163], v[200:203], v[22:25]
	v_mfma_f32_16x16x32_bf16 v[14:17], v[152:155], v[208:211], v[14:17]
	v_mfma_f32_16x16x32_bf16 v[6:9], v[160:163], v[208:211], v[6:9]
	s_setprio 0
	s_setprio 1
	v_mfma_f32_16x16x32_bf16 v[58:61], v[164:167], v[180:183], v[58:61]
	v_mfma_f32_16x16x32_bf16 v[50:53], v[172:175], v[180:183], v[50:53]
	v_mfma_f32_16x16x32_bf16 v[42:45], v[164:167], v[188:191], v[42:45]
	v_mfma_f32_16x16x32_bf16 v[34:37], v[172:175], v[188:191], v[34:37]
	v_mfma_f32_16x16x32_bf16 v[26:29], v[164:167], v[196:199], v[26:29]
	v_mfma_f32_16x16x32_bf16 v[18:21], v[172:175], v[196:199], v[18:21]
	v_mfma_f32_16x16x32_bf16 v[10:13], v[164:167], v[204:207], v[10:13]
	v_mfma_f32_16x16x32_bf16 v[2:5], v[172:175], v[204:207], v[2:5]
	v_mfma_f32_16x16x32_bf16 v[58:61], v[168:171], v[184:187], v[58:61]
	v_mfma_f32_16x16x32_bf16 v[50:53], v[176:179], v[184:187], v[50:53]
	v_mfma_f32_16x16x32_bf16 v[42:45], v[168:171], v[192:195], v[42:45]
	v_mfma_f32_16x16x32_bf16 v[34:37], v[176:179], v[192:195], v[34:37]
	v_mfma_f32_16x16x32_bf16 v[26:29], v[168:171], v[200:203], v[26:29]
	v_mfma_f32_16x16x32_bf16 v[18:21], v[176:179], v[200:203], v[18:21]
	v_mfma_f32_16x16x32_bf16 v[10:13], v[168:171], v[208:211], v[10:13]
	v_mfma_f32_16x16x32_bf16 v[2:5], v[176:179], v[208:211], v[2:5]
	s_setprio 0
	s_barrier
	s_add_i32 s69, s69, 2
	s_add_u32 s67, s67, 0x100
	s_addc_u32 s68, s68, 0
	s_add_u32 s50, s50, 0x100
	s_addc_u32 s51, s51, 0
	s_cmp_lt_u32 s69, 14
	s_cbranch_scc1 .LBB0_3212
	s_orn2_b64 vcc, s[44:45], s[10:11]
	s_and_b64 vcc, exec, vcc
	s_cbranch_vccnz .LBB0_3215
	s_barrier
.LBB0_3215:
	s_mov_b32 s98, 0xbfb8aa3b
	s_mov_b32 s99, 0xbfb8aa3b
	v_lshl_add_u32 v148, s48, 8, v1
	v_lshl_or_b32 v150, s49, 7, v142
	v_pk_mul_f32 v[230:231], v[126:127], s[98:99]
	v_exp_f32_e32 v230, v230
	v_exp_f32_e32 v231, v231
	v_add_f32_e32 v230, 1.0, v230
	v_add_f32_e32 v231, 1.0, v231
	v_rcp_f32_e32 v230, v230
	v_rcp_f32_e32 v231, v231
	v_mul_f32_e32 v234, v126, v230
	v_mul_f32_e32 v235, v127, v231
	v_pk_mul_f32 v[234:235], v[234:235], v[122:123]
	v_cvt_pk_bf16_f32 v122, v234, v235
	v_pk_mul_f32 v[230:231], v[128:129], s[98:99]
	v_exp_f32_e32 v230, v230
	v_exp_f32_e32 v231, v231
	v_add_f32_e32 v230, 1.0, v230
	v_add_f32_e32 v231, 1.0, v231
	v_rcp_f32_e32 v230, v230
	v_rcp_f32_e32 v231, v231
	v_mul_f32_e32 v236, v128, v230
	v_mul_f32_e32 v237, v129, v231
	v_pk_mul_f32 v[236:237], v[236:237], v[124:125]
	v_cvt_pk_bf16_f32 v123, v236, v237
	v_pk_mul_f32 v[230:231], v[118:119], s[98:99]
	v_exp_f32_e32 v230, v230
	v_exp_f32_e32 v231, v231
	v_add_f32_e32 v230, 1.0, v230
	v_add_f32_e32 v231, 1.0, v231
	v_rcp_f32_e32 v230, v230
	v_rcp_f32_e32 v231, v231
	v_mul_f32_e32 v238, v118, v230
	v_mul_f32_e32 v239, v119, v231
	v_pk_mul_f32 v[238:239], v[238:239], v[114:115]
	v_cvt_pk_bf16_f32 v124, v238, v239
	v_pk_mul_f32 v[230:231], v[120:121], s[98:99]
	v_exp_f32_e32 v230, v230
	v_exp_f32_e32 v231, v231
	v_add_f32_e32 v230, 1.0, v230
	v_add_f32_e32 v231, 1.0, v231
	v_rcp_f32_e32 v230, v230
	v_rcp_f32_e32 v231, v231
	v_mul_f32_e32 v240, v120, v230
	v_mul_f32_e32 v241, v121, v231
	v_pk_mul_f32 v[240:241], v[240:241], v[116:117]
	v_cvt_pk_bf16_f32 v125, v240, v241
	v_ashrrev_i32_e32 v151, 31, v150
	v_mov_b64_e32 v[114:115], s[22:23]
	v_mad_i64_i32 v[118:119], s[48:49], v148, s64, v[114:115]
	v_lshlrev_b64 v[116:117], 1, v[150:151]
	v_lshl_add_u64 v[118:119], v[118:119], 0, v[116:117]
	global_store_dwordx4 v[118:119], v[122:125], off
	s_nop 1
	v_pk_mul_f32 v[230:231], v[110:111], s[98:99]
	v_exp_f32_e32 v230, v230
	v_exp_f32_e32 v231, v231
	v_add_f32_e32 v230, 1.0, v230
	v_add_f32_e32 v231, 1.0, v231
	v_rcp_f32_e32 v230, v230
	v_rcp_f32_e32 v231, v231
	v_mul_f32_e32 v234, v110, v230
	v_mul_f32_e32 v235, v111, v231
	v_pk_mul_f32 v[234:235], v[234:235], v[106:107]
	v_cvt_pk_bf16_f32 v106, v234, v235
	v_pk_mul_f32 v[230:231], v[112:113], s[98:99]
	v_exp_f32_e32 v230, v230
	v_exp_f32_e32 v231, v231
	v_add_f32_e32 v230, 1.0, v230
	v_add_f32_e32 v231, 1.0, v231
	v_rcp_f32_e32 v230, v230
	v_rcp_f32_e32 v231, v231
	v_mul_f32_e32 v236, v112, v230
	v_mul_f32_e32 v237, v113, v231
	v_pk_mul_f32 v[236:237], v[236:237], v[108:109]
	v_cvt_pk_bf16_f32 v107, v236, v237
	v_pk_mul_f32 v[230:231], v[102:103], s[98:99]
	v_exp_f32_e32 v230, v230
	v_exp_f32_e32 v231, v231
	v_add_f32_e32 v230, 1.0, v230
	v_add_f32_e32 v231, 1.0, v231
	v_rcp_f32_e32 v230, v230
	v_rcp_f32_e32 v231, v231
	v_mul_f32_e32 v238, v102, v230
	v_mul_f32_e32 v239, v103, v231
	v_pk_mul_f32 v[238:239], v[238:239], v[98:99]
	v_cvt_pk_bf16_f32 v108, v238, v239
	v_pk_mul_f32 v[230:231], v[104:105], s[98:99]
	v_exp_f32_e32 v230, v230
	v_exp_f32_e32 v231, v231
	v_add_f32_e32 v230, 1.0, v230
	v_add_f32_e32 v231, 1.0, v231
	v_rcp_f32_e32 v230, v230
	v_rcp_f32_e32 v231, v231
	v_mul_f32_e32 v240, v104, v230
	v_mul_f32_e32 v241, v105, v231
	v_pk_mul_f32 v[240:241], v[240:241], v[100:101]
	v_cvt_pk_bf16_f32 v109, v240, v241
	v_or_b32_e32 v98, 16, v148
	v_mad_i64_i32 v[98:99], s[48:49], v98, s64, v[114:115]
	v_lshl_add_u64 v[98:99], v[98:99], 0, v[116:117]
	global_store_dwordx4 v[98:99], v[106:109], off
	v_pk_mul_f32 v[230:231], v[94:95], s[98:99]
	v_exp_f32_e32 v230, v230
	v_exp_f32_e32 v231, v231
	v_add_f32_e32 v230, 1.0, v230
	v_add_f32_e32 v231, 1.0, v231
	v_rcp_f32_e32 v230, v230
	v_rcp_f32_e32 v231, v231
	v_mul_f32_e32 v234, v94, v230
	v_mul_f32_e32 v235, v95, v231
	v_pk_mul_f32 v[234:235], v[234:235], v[90:91]
	v_cvt_pk_bf16_f32 v90, v234, v235
	v_pk_mul_f32 v[230:231], v[96:97], s[98:99]
	v_exp_f32_e32 v230, v230
	v_exp_f32_e32 v231, v231
	v_add_f32_e32 v230, 1.0, v230
	v_add_f32_e32 v231, 1.0, v231
	v_rcp_f32_e32 v230, v230
	v_rcp_f32_e32 v231, v231
	v_mul_f32_e32 v236, v96, v230
	v_mul_f32_e32 v237, v97, v231
	v_pk_mul_f32 v[236:237], v[236:237], v[92:93]
	v_cvt_pk_bf16_f32 v91, v236, v237
	v_pk_mul_f32 v[230:231], v[86:87], s[98:99]
	v_exp_f32_e32 v230, v230
	v_exp_f32_e32 v231, v231
	v_add_f32_e32 v230, 1.0, v230
	v_add_f32_e32 v231, 1.0, v231
	v_rcp_f32_e32 v230, v230
	v_rcp_f32_e32 v231, v231
	v_mul_f32_e32 v238, v86, v230
	v_mul_f32_e32 v239, v87, v231
	v_pk_mul_f32 v[238:239], v[238:239], v[82:83]
	v_cvt_pk_bf16_f32 v92, v238, v239
	v_pk_mul_f32 v[230:231], v[88:89], s[98:99]
	v_exp_f32_e32 v230, v230
	v_exp_f32_e32 v231, v231
	v_add_f32_e32 v230, 1.0, v230
	v_add_f32_e32 v231, 1.0, v231
	v_rcp_f32_e32 v230, v230
	v_rcp_f32_e32 v231, v231
	v_mul_f32_e32 v240, v88, v230
	v_mul_f32_e32 v241, v89, v231
	v_pk_mul_f32 v[240:241], v[240:241], v[84:85]
	v_cvt_pk_bf16_f32 v93, v240, v241
	v_or_b32_e32 v82, 32, v148
	v_mad_i64_i32 v[82:83], s[48:49], v82, s64, v[114:115]
	v_lshl_add_u64 v[82:83], v[82:83], 0, v[116:117]
	global_store_dwordx4 v[82:83], v[90:93], off
	v_pk_mul_f32 v[230:231], v[78:79], s[98:99]
	v_exp_f32_e32 v230, v230
	v_exp_f32_e32 v231, v231
	v_add_f32_e32 v230, 1.0, v230
	v_add_f32_e32 v231, 1.0, v231
	v_rcp_f32_e32 v230, v230
	v_rcp_f32_e32 v231, v231
	v_mul_f32_e32 v234, v78, v230
	v_mul_f32_e32 v235, v79, v231
	v_pk_mul_f32 v[234:235], v[234:235], v[74:75]
	v_cvt_pk_bf16_f32 v74, v234, v235
	v_pk_mul_f32 v[230:231], v[80:81], s[98:99]
	v_exp_f32_e32 v230, v230
	v_exp_f32_e32 v231, v231
	v_add_f32_e32 v230, 1.0, v230
	v_add_f32_e32 v231, 1.0, v231
	v_rcp_f32_e32 v230, v230
	v_rcp_f32_e32 v231, v231
	v_mul_f32_e32 v236, v80, v230
	v_mul_f32_e32 v237, v81, v231
	v_pk_mul_f32 v[236:237], v[236:237], v[76:77]
	v_cvt_pk_bf16_f32 v75, v236, v237
	v_pk_mul_f32 v[230:231], v[70:71], s[98:99]
	v_exp_f32_e32 v230, v230
	v_exp_f32_e32 v231, v231
	v_add_f32_e32 v230, 1.0, v230
	v_add_f32_e32 v231, 1.0, v231
	v_rcp_f32_e32 v230, v230
	v_rcp_f32_e32 v231, v231
	v_mul_f32_e32 v238, v70, v230
	v_mul_f32_e32 v239, v71, v231
	v_pk_mul_f32 v[238:239], v[238:239], v[66:67]
	v_cvt_pk_bf16_f32 v76, v238, v239
	v_pk_mul_f32 v[230:231], v[72:73], s[98:99]
	v_exp_f32_e32 v230, v230
	v_exp_f32_e32 v231, v231
	v_add_f32_e32 v230, 1.0, v230
	v_add_f32_e32 v231, 1.0, v231
	v_rcp_f32_e32 v230, v230
	v_rcp_f32_e32 v231, v231
	v_mul_f32_e32 v240, v72, v230
	v_mul_f32_e32 v241, v73, v231
	v_pk_mul_f32 v[240:241], v[240:241], v[68:69]
	v_cvt_pk_bf16_f32 v77, v240, v241
	v_or_b32_e32 v66, 48, v148
	v_mad_i64_i32 v[66:67], s[48:49], v66, s64, v[114:115]
	v_lshl_add_u64 v[66:67], v[66:67], 0, v[116:117]
	global_store_dwordx4 v[66:67], v[74:77], off
	v_pk_mul_f32 v[230:231], v[62:63], s[98:99]
	v_exp_f32_e32 v230, v230
	v_exp_f32_e32 v231, v231
	v_add_f32_e32 v230, 1.0, v230
	v_add_f32_e32 v231, 1.0, v231
	v_rcp_f32_e32 v230, v230
	v_rcp_f32_e32 v231, v231
	v_mul_f32_e32 v234, v62, v230
	v_mul_f32_e32 v235, v63, v231
	v_pk_mul_f32 v[234:235], v[234:235], v[58:59]
	v_cvt_pk_bf16_f32 v58, v234, v235
	v_pk_mul_f32 v[230:231], v[64:65], s[98:99]
	v_exp_f32_e32 v230, v230
	v_exp_f32_e32 v231, v231
	v_add_f32_e32 v230, 1.0, v230
	v_add_f32_e32 v231, 1.0, v231
	v_rcp_f32_e32 v230, v230
	v_rcp_f32_e32 v231, v231
	v_mul_f32_e32 v236, v64, v230
	v_mul_f32_e32 v237, v65, v231
	v_pk_mul_f32 v[236:237], v[236:237], v[60:61]
	v_cvt_pk_bf16_f32 v59, v236, v237
	v_pk_mul_f32 v[230:231], v[54:55], s[98:99]
	v_exp_f32_e32 v230, v230
	v_exp_f32_e32 v231, v231
	v_add_f32_e32 v230, 1.0, v230
	v_add_f32_e32 v231, 1.0, v231
	v_rcp_f32_e32 v230, v230
	v_rcp_f32_e32 v231, v231
	v_mul_f32_e32 v238, v54, v230
	v_mul_f32_e32 v239, v55, v231
	v_pk_mul_f32 v[238:239], v[238:239], v[50:51]
	v_cvt_pk_bf16_f32 v60, v238, v239
	v_pk_mul_f32 v[230:231], v[56:57], s[98:99]
	v_exp_f32_e32 v230, v230
	v_exp_f32_e32 v231, v231
	v_add_f32_e32 v230, 1.0, v230
	v_add_f32_e32 v231, 1.0, v231
	v_rcp_f32_e32 v230, v230
	v_rcp_f32_e32 v231, v231
	v_mul_f32_e32 v240, v56, v230
	v_mul_f32_e32 v241, v57, v231
	v_pk_mul_f32 v[240:241], v[240:241], v[52:53]
	v_add_u32_e32 v66, 0x80, v148
	v_cvt_pk_bf16_f32 v61, v240, v241
	v_mad_i64_i32 v[50:51], s[48:49], v66, s64, v[114:115]
	v_lshl_add_u64 v[50:51], v[50:51], 0, v[116:117]
	global_store_dwordx4 v[50:51], v[58:61], off
	v_pk_mul_f32 v[230:231], v[46:47], s[98:99]
	v_exp_f32_e32 v230, v230
	v_exp_f32_e32 v231, v231
	v_add_f32_e32 v230, 1.0, v230
	v_add_f32_e32 v231, 1.0, v231
	v_rcp_f32_e32 v230, v230
	v_rcp_f32_e32 v231, v231
	v_mul_f32_e32 v234, v46, v230
	v_mul_f32_e32 v235, v47, v231
	v_pk_mul_f32 v[234:235], v[234:235], v[42:43]
	v_cvt_pk_bf16_f32 v42, v234, v235
	v_pk_mul_f32 v[230:231], v[48:49], s[98:99]
	v_exp_f32_e32 v230, v230
	v_exp_f32_e32 v231, v231
	v_add_f32_e32 v230, 1.0, v230
	v_add_f32_e32 v231, 1.0, v231
	v_rcp_f32_e32 v230, v230
	v_rcp_f32_e32 v231, v231
	v_mul_f32_e32 v236, v48, v230
	v_mul_f32_e32 v237, v49, v231
	v_pk_mul_f32 v[236:237], v[236:237], v[44:45]
	v_cvt_pk_bf16_f32 v43, v236, v237
	v_pk_mul_f32 v[230:231], v[38:39], s[98:99]
	v_exp_f32_e32 v230, v230
	v_exp_f32_e32 v231, v231
	v_add_f32_e32 v230, 1.0, v230
	v_add_f32_e32 v231, 1.0, v231
	v_rcp_f32_e32 v230, v230
	v_rcp_f32_e32 v231, v231
	v_mul_f32_e32 v238, v38, v230
	v_mul_f32_e32 v239, v39, v231
	v_pk_mul_f32 v[238:239], v[238:239], v[34:35]
	v_cvt_pk_bf16_f32 v44, v238, v239
	v_pk_mul_f32 v[230:231], v[40:41], s[98:99]
	v_exp_f32_e32 v230, v230
	v_exp_f32_e32 v231, v231
	v_add_f32_e32 v230, 1.0, v230
	v_add_f32_e32 v231, 1.0, v231
	v_rcp_f32_e32 v230, v230
	v_rcp_f32_e32 v231, v231
	v_mul_f32_e32 v240, v40, v230
	v_mul_f32_e32 v241, v41, v231
	v_pk_mul_f32 v[240:241], v[240:241], v[36:37]
	v_cvt_pk_bf16_f32 v45, v240, v241
	v_add_u32_e32 v34, 0x90, v148
	v_mad_i64_i32 v[34:35], s[48:49], v34, s64, v[114:115]
	v_lshl_add_u64 v[34:35], v[34:35], 0, v[116:117]
	global_store_dwordx4 v[34:35], v[42:45], off
	v_pk_mul_f32 v[230:231], v[30:31], s[98:99]
	v_exp_f32_e32 v230, v230
	v_exp_f32_e32 v231, v231
	v_add_f32_e32 v230, 1.0, v230
	v_add_f32_e32 v231, 1.0, v231
	v_rcp_f32_e32 v230, v230
	v_rcp_f32_e32 v231, v231
	v_mul_f32_e32 v234, v30, v230
	v_mul_f32_e32 v235, v31, v231
	v_pk_mul_f32 v[234:235], v[234:235], v[26:27]
	v_cvt_pk_bf16_f32 v26, v234, v235
	v_pk_mul_f32 v[230:231], v[32:33], s[98:99]
	v_exp_f32_e32 v230, v230
	v_exp_f32_e32 v231, v231
	v_add_f32_e32 v230, 1.0, v230
	v_add_f32_e32 v231, 1.0, v231
	v_rcp_f32_e32 v230, v230
	v_rcp_f32_e32 v231, v231
	v_mul_f32_e32 v236, v32, v230
	v_mul_f32_e32 v237, v33, v231
	v_pk_mul_f32 v[236:237], v[236:237], v[28:29]
	v_cvt_pk_bf16_f32 v27, v236, v237
	v_pk_mul_f32 v[230:231], v[22:23], s[98:99]
	v_exp_f32_e32 v230, v230
	v_exp_f32_e32 v231, v231
	v_add_f32_e32 v230, 1.0, v230
	v_add_f32_e32 v231, 1.0, v231
	v_rcp_f32_e32 v230, v230
	v_rcp_f32_e32 v231, v231
	v_mul_f32_e32 v238, v22, v230
	v_mul_f32_e32 v239, v23, v231
	v_pk_mul_f32 v[238:239], v[238:239], v[18:19]
	v_cvt_pk_bf16_f32 v28, v238, v239
	v_pk_mul_f32 v[230:231], v[24:25], s[98:99]
	v_exp_f32_e32 v230, v230
	v_exp_f32_e32 v231, v231
	v_add_f32_e32 v230, 1.0, v230
	v_add_f32_e32 v231, 1.0, v231
	v_rcp_f32_e32 v230, v230
	v_rcp_f32_e32 v231, v231
	v_mul_f32_e32 v240, v24, v230
	v_mul_f32_e32 v241, v25, v231
	v_pk_mul_f32 v[240:241], v[240:241], v[20:21]
	v_cvt_pk_bf16_f32 v29, v240, v241
	v_add_u32_e32 v18, 0xa0, v148
	v_mad_i64_i32 v[18:19], s[48:49], v18, s64, v[114:115]
	v_lshl_add_u64 v[18:19], v[18:19], 0, v[116:117]
	global_store_dwordx4 v[18:19], v[26:29], off
	v_pk_mul_f32 v[230:231], v[14:15], s[98:99]
	v_exp_f32_e32 v230, v230
	v_exp_f32_e32 v231, v231
	v_add_f32_e32 v230, 1.0, v230
	v_add_f32_e32 v231, 1.0, v231
	v_rcp_f32_e32 v230, v230
	v_rcp_f32_e32 v231, v231
	v_mul_f32_e32 v234, v14, v230
	v_mul_f32_e32 v235, v15, v231
	v_pk_mul_f32 v[234:235], v[234:235], v[10:11]
	v_cvt_pk_bf16_f32 v10, v234, v235
	v_pk_mul_f32 v[230:231], v[16:17], s[98:99]
	v_exp_f32_e32 v230, v230
	v_exp_f32_e32 v231, v231
	v_add_f32_e32 v230, 1.0, v230
	v_add_f32_e32 v231, 1.0, v231
	v_rcp_f32_e32 v230, v230
	v_rcp_f32_e32 v231, v231
	v_mul_f32_e32 v236, v16, v230
	v_mul_f32_e32 v237, v17, v231
	v_pk_mul_f32 v[236:237], v[236:237], v[12:13]
	v_cvt_pk_bf16_f32 v11, v236, v237
	v_pk_mul_f32 v[230:231], v[6:7], s[98:99]
	v_exp_f32_e32 v230, v230
	v_exp_f32_e32 v231, v231
	v_add_f32_e32 v230, 1.0, v230
	v_add_f32_e32 v231, 1.0, v231
	v_rcp_f32_e32 v230, v230
	v_rcp_f32_e32 v231, v231
	v_mul_f32_e32 v238, v6, v230
	v_mul_f32_e32 v239, v7, v231
	v_pk_mul_f32 v[238:239], v[238:239], v[2:3]
	v_cvt_pk_bf16_f32 v12, v238, v239
	v_pk_mul_f32 v[230:231], v[8:9], s[98:99]
	v_exp_f32_e32 v230, v230
	v_exp_f32_e32 v231, v231
	v_add_f32_e32 v230, 1.0, v230
	v_add_f32_e32 v231, 1.0, v231
	v_rcp_f32_e32 v230, v230
	v_rcp_f32_e32 v231, v231
	v_mul_f32_e32 v240, v8, v230
	v_mul_f32_e32 v241, v9, v231
	v_pk_mul_f32 v[240:241], v[240:241], v[4:5]
	v_cvt_pk_bf16_f32 v13, v240, v241
	v_add_u32_e32 v2, 0xb0, v148
	v_mad_i64_i32 v[2:3], s[48:49], v2, s64, v[114:115]
	v_lshl_add_u64 v[2:3], v[2:3], 0, v[116:117]
	s_mov_b64 s[48:49], -1
	s_and_b64 vcc, exec, s[44:45]
	global_store_dwordx4 v[2:3], v[10:13], off
	s_cbranch_vccz .LBB0_3204
	s_andn2_b64 vcc, exec, s[6:7]
	s_cbranch_vccnz .LBB0_3203
	s_nop 0
	s_branch .LBB0_3203

.LBB0_3467:
	ds_read_b128 v[150:153], v133
	ds_read_b128 v[154:157], v133 offset:1024
	ds_read_b128 v[158:161], v133 offset:2048
	ds_read_b128 v[162:165], v133 offset:3072
	ds_read_b128 v[166:169], v146
	ds_read_b128 v[170:173], v146 offset:1024
	ds_read_b128 v[174:177], v146 offset:2048
	ds_read_b128 v[178:181], v146 offset:3072
	s_add_u32 s56, s54, 0xfffc0080
	s_addc_u32 s57, s55, -1
	s_cmp_eq_u32 s68, 12
	s_cselect_b32 s59, s45, s57
	s_cselect_b32 s58, s64, s56
	s_cselect_b32 s57, s25, s67
	s_cselect_b32 s56, s65, s66
	v_lshl_add_u64 v[214:215], s[54:55], 0, v[144:145]
	s_add_i32 m0, s31, 0xc000
	ds_read_b128 v[182:185], v147
	ds_read_b128 v[186:189], v147 offset:1024
	ds_read_b128 v[190:193], v147 offset:2048
	ds_read_b128 v[194:197], v147 offset:3072
	ds_read_b128 v[198:201], v147 offset:4096
	ds_read_b128 v[202:205], v147 offset:5120
	ds_read_b128 v[206:209], v147 offset:6144
	ds_read_b128 v[210:213], v147 offset:7168
	global_load_lds_dwordx4 v[214:215], off
	v_lshl_add_u64 v[214:215], s[54:55], 0, v[142:143]
	s_add_i32 m0, s31, 0xe000
	s_nop 0
	global_load_lds_dwordx4 v[214:215], off
	s_waitcnt vmcnt(8)
	s_waitcnt lgkmcnt(0)
	s_barrier
	s_setprio 1
	s_waitcnt lgkmcnt(0)
	v_mfma_f32_16x16x32_bf16 v[126:129], v[150:153], v[182:185], v[126:129]
	v_mfma_f32_16x16x32_bf16 v[118:121], v[158:161], v[182:185], v[118:121]
	v_mfma_f32_16x16x32_bf16 v[110:113], v[150:153], v[190:193], v[110:113]
	v_mfma_f32_16x16x32_bf16 v[102:105], v[158:161], v[190:193], v[102:105]
	v_mfma_f32_16x16x32_bf16 v[94:97], v[150:153], v[198:201], v[94:97]
	v_mfma_f32_16x16x32_bf16 v[86:89], v[158:161], v[198:201], v[86:89]
	v_mfma_f32_16x16x32_bf16 v[78:81], v[150:153], v[206:209], v[78:81]
	v_mfma_f32_16x16x32_bf16 v[70:73], v[158:161], v[206:209], v[70:73]
	v_mfma_f32_16x16x32_bf16 v[126:129], v[154:157], v[186:189], v[126:129]
	v_mfma_f32_16x16x32_bf16 v[118:121], v[162:165], v[186:189], v[118:121]
	v_mfma_f32_16x16x32_bf16 v[110:113], v[154:157], v[194:197], v[110:113]
	v_mfma_f32_16x16x32_bf16 v[102:105], v[162:165], v[194:197], v[102:105]
	v_mfma_f32_16x16x32_bf16 v[94:97], v[154:157], v[202:205], v[94:97]
	v_mfma_f32_16x16x32_bf16 v[86:89], v[162:165], v[202:205], v[86:89]
	v_mfma_f32_16x16x32_bf16 v[78:81], v[154:157], v[210:213], v[78:81]
	v_mfma_f32_16x16x32_bf16 v[70:73], v[162:165], v[210:213], v[70:73]
	s_setprio 0
	s_setprio 1
	v_mfma_f32_16x16x32_bf16 v[122:125], v[166:169], v[182:185], v[122:125]
	v_mfma_f32_16x16x32_bf16 v[114:117], v[174:177], v[182:185], v[114:117]
	v_mfma_f32_16x16x32_bf16 v[106:109], v[166:169], v[190:193], v[106:109]
	v_mfma_f32_16x16x32_bf16 v[98:101], v[174:177], v[190:193], v[98:101]
	v_mfma_f32_16x16x32_bf16 v[90:93], v[166:169], v[198:201], v[90:93]
	v_mfma_f32_16x16x32_bf16 v[82:85], v[174:177], v[198:201], v[82:85]
	v_mfma_f32_16x16x32_bf16 v[74:77], v[166:169], v[206:209], v[74:77]
	v_mfma_f32_16x16x32_bf16 v[66:69], v[174:177], v[206:209], v[66:69]
	v_mfma_f32_16x16x32_bf16 v[122:125], v[170:173], v[186:189], v[122:125]
	v_mfma_f32_16x16x32_bf16 v[114:117], v[178:181], v[186:189], v[114:117]
	v_mfma_f32_16x16x32_bf16 v[106:109], v[170:173], v[194:197], v[106:109]
	v_mfma_f32_16x16x32_bf16 v[98:101], v[178:181], v[194:197], v[98:101]
	v_mfma_f32_16x16x32_bf16 v[90:93], v[170:173], v[202:205], v[90:93]
	v_mfma_f32_16x16x32_bf16 v[82:85], v[178:181], v[202:205], v[82:85]
	v_mfma_f32_16x16x32_bf16 v[74:77], v[170:173], v[210:213], v[74:77]
	v_mfma_f32_16x16x32_bf16 v[66:69], v[178:181], v[210:213], v[66:69]
	s_setprio 0
	s_barrier
	s_mov_b32 m0, s27
	v_lshl_add_u64 v[214:215], s[56:57], 0, v[136:137]
	s_add_u32 s70, s56, 0x40000
	ds_read_b128 v[182:185], v147 offset:16384
	ds_read_b128 v[186:189], v147 offset:17408
	ds_read_b128 v[190:193], v147 offset:18432
	ds_read_b128 v[194:197], v147 offset:19456
	ds_read_b128 v[198:201], v147 offset:20480
	ds_read_b128 v[202:205], v147 offset:21504
	ds_read_b128 v[206:209], v147 offset:22528
	ds_read_b128 v[210:213], v147 offset:23552
	global_load_lds_dwordx4 v[214:215], off
	v_lshl_add_u64 v[216:217], s[56:57], 0, v[140:141]
	s_mov_b32 m0, s28
	s_addc_u32 s71, s57, 0
	global_load_lds_dwordx4 v[216:217], off
	v_lshl_add_u64 v[218:219], s[70:71], 0, v[136:137]
	s_mov_b32 m0, s29
	v_lshl_add_u64 v[220:221], s[58:59], 0, v[138:139]
	global_load_lds_dwordx4 v[218:219], off
	v_lshl_add_u64 v[218:219], s[70:71], 0, v[140:141]
	s_mov_b32 m0, s30
	s_nop 0
	global_load_lds_dwordx4 v[218:219], off
	v_lshl_add_u64 v[218:219], s[58:59], 0, v[134:135]
	s_mov_b32 m0, s31
	s_nop 0
	global_load_lds_dwordx4 v[218:219], off
	s_mov_b32 m0, s33
	s_nop 0
	global_load_lds_dwordx4 v[220:221], off
	s_waitcnt vmcnt(8)
	s_waitcnt lgkmcnt(0)
	s_barrier
	s_setprio 1
	s_waitcnt lgkmcnt(0)
	v_mfma_f32_16x16x32_bf16 v[62:65], v[150:153], v[182:185], v[62:65]
	v_mfma_f32_16x16x32_bf16 v[54:57], v[158:161], v[182:185], v[54:57]
	v_mfma_f32_16x16x32_bf16 v[46:49], v[150:153], v[190:193], v[46:49]
	v_mfma_f32_16x16x32_bf16 v[38:41], v[158:161], v[190:193], v[38:41]
	v_mfma_f32_16x16x32_bf16 v[30:33], v[150:153], v[198:201], v[30:33]
	v_mfma_f32_16x16x32_bf16 v[22:25], v[158:161], v[198:201], v[22:25]
	v_mfma_f32_16x16x32_bf16 v[14:17], v[150:153], v[206:209], v[14:17]
	v_mfma_f32_16x16x32_bf16 v[6:9], v[158:161], v[206:209], v[6:9]
	v_mfma_f32_16x16x32_bf16 v[62:65], v[154:157], v[186:189], v[62:65]
	v_mfma_f32_16x16x32_bf16 v[54:57], v[162:165], v[186:189], v[54:57]
	v_mfma_f32_16x16x32_bf16 v[46:49], v[154:157], v[194:197], v[46:49]
	v_mfma_f32_16x16x32_bf16 v[38:41], v[162:165], v[194:197], v[38:41]
	v_mfma_f32_16x16x32_bf16 v[30:33], v[154:157], v[202:205], v[30:33]
	v_mfma_f32_16x16x32_bf16 v[22:25], v[162:165], v[202:205], v[22:25]
	v_mfma_f32_16x16x32_bf16 v[14:17], v[154:157], v[210:213], v[14:17]
	v_mfma_f32_16x16x32_bf16 v[6:9], v[162:165], v[210:213], v[6:9]
	s_setprio 0
	s_setprio 1
	v_mfma_f32_16x16x32_bf16 v[58:61], v[166:169], v[182:185], v[58:61]
	v_mfma_f32_16x16x32_bf16 v[50:53], v[174:177], v[182:185], v[50:53]
	v_mfma_f32_16x16x32_bf16 v[42:45], v[166:169], v[190:193], v[42:45]
	v_mfma_f32_16x16x32_bf16 v[34:37], v[174:177], v[190:193], v[34:37]
	v_mfma_f32_16x16x32_bf16 v[26:29], v[166:169], v[198:201], v[26:29]
	v_mfma_f32_16x16x32_bf16 v[18:21], v[174:177], v[198:201], v[18:21]
	v_mfma_f32_16x16x32_bf16 v[10:13], v[166:169], v[206:209], v[10:13]
	v_mfma_f32_16x16x32_bf16 v[2:5], v[174:177], v[206:209], v[2:5]
	v_mfma_f32_16x16x32_bf16 v[58:61], v[170:173], v[186:189], v[58:61]
	v_mfma_f32_16x16x32_bf16 v[50:53], v[178:181], v[186:189], v[50:53]
	v_mfma_f32_16x16x32_bf16 v[42:45], v[170:173], v[194:197], v[42:45]
	v_mfma_f32_16x16x32_bf16 v[34:37], v[178:181], v[194:197], v[34:37]
	v_mfma_f32_16x16x32_bf16 v[26:29], v[170:173], v[202:205], v[26:29]
	v_mfma_f32_16x16x32_bf16 v[18:21], v[178:181], v[202:205], v[18:21]
	v_mfma_f32_16x16x32_bf16 v[10:13], v[170:173], v[210:213], v[10:13]
	v_mfma_f32_16x16x32_bf16 v[2:5], v[178:181], v[210:213], v[2:5]
	s_setprio 0
	s_barrier
	ds_read_b128 v[150:153], v148
	ds_read_b128 v[154:157], v148 offset:1024
	ds_read_b128 v[158:161], v148 offset:2048
	ds_read_b128 v[162:165], v148 offset:3072
	ds_read_b128 v[166:169], v149
	ds_read_b128 v[170:173], v149 offset:1024
	ds_read_b128 v[174:177], v149 offset:2048
	ds_read_b128 v[178:181], v149 offset:3072
	s_add_u32 s58, s58, 0x40000
	s_addc_u32 s59, s59, 0
	s_mov_b32 m0, s34
	v_lshl_add_u64 v[222:223], s[58:59], 0, v[134:135]
	ds_read_b128 v[182:185], v147 offset:32768
	ds_read_b128 v[186:189], v147 offset:33792
	ds_read_b128 v[190:193], v147 offset:34816
	ds_read_b128 v[194:197], v147 offset:35840
	ds_read_b128 v[198:201], v147 offset:36864
	ds_read_b128 v[202:205], v147 offset:37888
	ds_read_b128 v[206:209], v147 offset:38912
	ds_read_b128 v[210:213], v147 offset:39936
	global_load_lds_dwordx4 v[222:223], off
	v_lshl_add_u64 v[222:223], s[58:59], 0, v[138:139]
	s_mov_b32 m0, s35
	s_nop 0
	global_load_lds_dwordx4 v[222:223], off
	s_waitcnt vmcnt(8)
	s_waitcnt lgkmcnt(0)
	s_barrier
	s_setprio 1
	s_waitcnt lgkmcnt(0)
	v_mfma_f32_16x16x32_bf16 v[126:129], v[150:153], v[182:185], v[126:129]
	v_mfma_f32_16x16x32_bf16 v[118:121], v[158:161], v[182:185], v[118:121]
	v_mfma_f32_16x16x32_bf16 v[110:113], v[150:153], v[190:193], v[110:113]
	v_mfma_f32_16x16x32_bf16 v[102:105], v[158:161], v[190:193], v[102:105]
	v_mfma_f32_16x16x32_bf16 v[94:97], v[150:153], v[198:201], v[94:97]
	v_mfma_f32_16x16x32_bf16 v[86:89], v[158:161], v[198:201], v[86:89]
	v_mfma_f32_16x16x32_bf16 v[78:81], v[150:153], v[206:209], v[78:81]
	v_mfma_f32_16x16x32_bf16 v[70:73], v[158:161], v[206:209], v[70:73]
	v_mfma_f32_16x16x32_bf16 v[126:129], v[154:157], v[186:189], v[126:129]
	v_mfma_f32_16x16x32_bf16 v[118:121], v[162:165], v[186:189], v[118:121]
	v_mfma_f32_16x16x32_bf16 v[110:113], v[154:157], v[194:197], v[110:113]
	v_mfma_f32_16x16x32_bf16 v[102:105], v[162:165], v[194:197], v[102:105]
	v_mfma_f32_16x16x32_bf16 v[94:97], v[154:157], v[202:205], v[94:97]
	v_mfma_f32_16x16x32_bf16 v[86:89], v[162:165], v[202:205], v[86:89]
	v_mfma_f32_16x16x32_bf16 v[78:81], v[154:157], v[210:213], v[78:81]
	v_mfma_f32_16x16x32_bf16 v[70:73], v[162:165], v[210:213], v[70:73]
	s_setprio 0
	s_setprio 1
	v_mfma_f32_16x16x32_bf16 v[122:125], v[166:169], v[182:185], v[122:125]
	v_mfma_f32_16x16x32_bf16 v[114:117], v[174:177], v[182:185], v[114:117]
	v_mfma_f32_16x16x32_bf16 v[106:109], v[166:169], v[190:193], v[106:109]
	v_mfma_f32_16x16x32_bf16 v[98:101], v[174:177], v[190:193], v[98:101]
	v_mfma_f32_16x16x32_bf16 v[90:93], v[166:169], v[198:201], v[90:93]
	v_mfma_f32_16x16x32_bf16 v[82:85], v[174:177], v[198:201], v[82:85]
	v_mfma_f32_16x16x32_bf16 v[74:77], v[166:169], v[206:209], v[74:77]
	v_mfma_f32_16x16x32_bf16 v[66:69], v[174:177], v[206:209], v[66:69]
	v_mfma_f32_16x16x32_bf16 v[122:125], v[170:173], v[186:189], v[122:125]
	v_mfma_f32_16x16x32_bf16 v[114:117], v[178:181], v[186:189], v[114:117]
	v_mfma_f32_16x16x32_bf16 v[106:109], v[170:173], v[194:197], v[106:109]
	v_mfma_f32_16x16x32_bf16 v[98:101], v[178:181], v[194:197], v[98:101]
	v_mfma_f32_16x16x32_bf16 v[90:93], v[170:173], v[202:205], v[90:93]
	v_mfma_f32_16x16x32_bf16 v[82:85], v[178:181], v[202:205], v[82:85]
	v_mfma_f32_16x16x32_bf16 v[74:77], v[170:173], v[210:213], v[74:77]
	v_mfma_f32_16x16x32_bf16 v[66:69], v[178:181], v[210:213], v[66:69]
	s_setprio 0
	s_barrier
	s_mov_b32 m0, s37
	v_lshl_add_u64 v[214:215], v[214:215], 0, s[8:9]
	s_add_u32 s56, s56, 0x40080
	ds_read_b128 v[182:185], v147 offset:49152
	ds_read_b128 v[186:189], v147 offset:50176
	ds_read_b128 v[190:193], v147 offset:51200
	ds_read_b128 v[194:197], v147 offset:52224
	ds_read_b128 v[198:201], v147 offset:53248
	ds_read_b128 v[202:205], v147 offset:54272
	ds_read_b128 v[206:209], v147 offset:55296
	ds_read_b128 v[210:213], v147 offset:56320
	global_load_lds_dwordx4 v[214:215], off
	v_lshl_add_u64 v[214:215], v[216:217], 0, s[8:9]
	s_mov_b32 m0, s41
	s_addc_u32 s57, s57, 0
	global_load_lds_dwordx4 v[214:215], off
	v_lshl_add_u64 v[214:215], s[56:57], 0, v[136:137]
	s_mov_b32 m0, s60
	s_nop 0
	global_load_lds_dwordx4 v[214:215], off
	v_lshl_add_u64 v[214:215], s[56:57], 0, v[140:141]
	s_mov_b32 m0, s61
	s_nop 0
	global_load_lds_dwordx4 v[214:215], off
	v_lshl_add_u64 v[214:215], v[218:219], 0, s[8:9]
	s_mov_b32 m0, s42
	s_nop 0
	global_load_lds_dwordx4 v[214:215], off
	v_lshl_add_u64 v[214:215], v[220:221], 0, s[8:9]
	s_mov_b32 m0, s43
	s_nop 0
	global_load_lds_dwordx4 v[214:215], off
	s_waitcnt vmcnt(8)
	s_waitcnt lgkmcnt(0)
	s_barrier
	s_setprio 1
	s_waitcnt lgkmcnt(0)
	v_mfma_f32_16x16x32_bf16 v[62:65], v[150:153], v[182:185], v[62:65]
	v_mfma_f32_16x16x32_bf16 v[54:57], v[158:161], v[182:185], v[54:57]
	v_mfma_f32_16x16x32_bf16 v[46:49], v[150:153], v[190:193], v[46:49]
	v_mfma_f32_16x16x32_bf16 v[38:41], v[158:161], v[190:193], v[38:41]
	v_mfma_f32_16x16x32_bf16 v[30:33], v[150:153], v[198:201], v[30:33]
	v_mfma_f32_16x16x32_bf16 v[22:25], v[158:161], v[198:201], v[22:25]
	v_mfma_f32_16x16x32_bf16 v[14:17], v[150:153], v[206:209], v[14:17]
	v_mfma_f32_16x16x32_bf16 v[6:9], v[158:161], v[206:209], v[6:9]
	v_mfma_f32_16x16x32_bf16 v[62:65], v[154:157], v[186:189], v[62:65]
	v_mfma_f32_16x16x32_bf16 v[54:57], v[162:165], v[186:189], v[54:57]
	v_mfma_f32_16x16x32_bf16 v[46:49], v[154:157], v[194:197], v[46:49]
	v_mfma_f32_16x16x32_bf16 v[38:41], v[162:165], v[194:197], v[38:41]
	v_mfma_f32_16x16x32_bf16 v[30:33], v[154:157], v[202:205], v[30:33]
	v_mfma_f32_16x16x32_bf16 v[22:25], v[162:165], v[202:205], v[22:25]
	v_mfma_f32_16x16x32_bf16 v[14:17], v[154:157], v[210:213], v[14:17]
	v_mfma_f32_16x16x32_bf16 v[6:9], v[162:165], v[210:213], v[6:9]
	s_setprio 0
	s_setprio 1
	v_mfma_f32_16x16x32_bf16 v[58:61], v[166:169], v[182:185], v[58:61]
	v_mfma_f32_16x16x32_bf16 v[50:53], v[174:177], v[182:185], v[50:53]
	v_mfma_f32_16x16x32_bf16 v[42:45], v[166:169], v[190:193], v[42:45]
	v_mfma_f32_16x16x32_bf16 v[34:37], v[174:177], v[190:193], v[34:37]
	v_mfma_f32_16x16x32_bf16 v[26:29], v[166:169], v[198:201], v[26:29]
	v_mfma_f32_16x16x32_bf16 v[18:21], v[174:177], v[198:201], v[18:21]
	v_mfma_f32_16x16x32_bf16 v[10:13], v[166:169], v[206:209], v[10:13]
	v_mfma_f32_16x16x32_bf16 v[2:5], v[174:177], v[206:209], v[2:5]
	v_mfma_f32_16x16x32_bf16 v[58:61], v[170:173], v[186:189], v[58:61]
	v_mfma_f32_16x16x32_bf16 v[50:53], v[178:181], v[186:189], v[50:53]
	v_mfma_f32_16x16x32_bf16 v[42:45], v[170:173], v[194:197], v[42:45]
	v_mfma_f32_16x16x32_bf16 v[34:37], v[178:181], v[194:197], v[34:37]
	v_mfma_f32_16x16x32_bf16 v[26:29], v[170:173], v[202:205], v[26:29]
	v_mfma_f32_16x16x32_bf16 v[18:21], v[178:181], v[202:205], v[18:21]
	v_mfma_f32_16x16x32_bf16 v[10:13], v[170:173], v[210:213], v[10:13]
	v_mfma_f32_16x16x32_bf16 v[2:5], v[178:181], v[210:213], v[2:5]
	s_setprio 0
	s_barrier
	s_add_i32 s68, s68, 2
	s_add_u32 s66, s66, 0x100
	s_addc_u32 s67, s67, 0
	s_add_u32 s54, s54, 0x100
	s_addc_u32 s55, s55, 0
	s_cmp_lt_u32 s68, 14
	s_cbranch_scc1 .LBB0_3467
	s_orn2_b64 vcc, s[48:49], s[10:11]
	s_and_b64 vcc, exec, vcc
	s_cbranch_vccnz .LBB0_3470
	s_barrier
.LBB0_3470:
	s_mov_b32 s98, 0xbfb8aa3b
	s_mov_b32 s99, 0xbfb8aa3b
	v_lshl_add_u32 v150, s52, 8, v1
	v_lshl_or_b32 v152, s53, 7, v131
	v_pk_mul_f32 v[230:231], v[126:127], s[98:99]
	v_exp_f32_e32 v230, v230
	v_exp_f32_e32 v231, v231
	v_add_f32_e32 v230, 1.0, v230
	v_add_f32_e32 v231, 1.0, v231
	v_rcp_f32_e32 v230, v230
	v_rcp_f32_e32 v231, v231
	v_mul_f32_e32 v234, v126, v230
	v_mul_f32_e32 v235, v127, v231
	v_pk_mul_f32 v[234:235], v[234:235], v[122:123]
	v_cvt_pk_bf16_f32 v122, v234, v235
	v_pk_mul_f32 v[230:231], v[128:129], s[98:99]
	v_exp_f32_e32 v230, v230
	v_exp_f32_e32 v231, v231
	v_add_f32_e32 v230, 1.0, v230
	v_add_f32_e32 v231, 1.0, v231
	v_rcp_f32_e32 v230, v230
	v_rcp_f32_e32 v231, v231
	v_mul_f32_e32 v236, v128, v230
	v_mul_f32_e32 v237, v129, v231
	v_pk_mul_f32 v[236:237], v[236:237], v[124:125]
	v_cvt_pk_bf16_f32 v123, v236, v237
	v_pk_mul_f32 v[230:231], v[118:119], s[98:99]
	v_exp_f32_e32 v230, v230
	v_exp_f32_e32 v231, v231
	v_add_f32_e32 v230, 1.0, v230
	v_add_f32_e32 v231, 1.0, v231
	v_rcp_f32_e32 v230, v230
	v_rcp_f32_e32 v231, v231
	v_mul_f32_e32 v238, v118, v230
	v_mul_f32_e32 v239, v119, v231
	v_pk_mul_f32 v[238:239], v[238:239], v[114:115]
	v_cvt_pk_bf16_f32 v124, v238, v239
	v_pk_mul_f32 v[230:231], v[120:121], s[98:99]
	v_exp_f32_e32 v230, v230
	v_exp_f32_e32 v231, v231
	v_add_f32_e32 v230, 1.0, v230
	v_add_f32_e32 v231, 1.0, v231
	v_rcp_f32_e32 v230, v230
	v_rcp_f32_e32 v231, v231
	v_mul_f32_e32 v240, v120, v230
	v_mul_f32_e32 v241, v121, v231
	v_pk_mul_f32 v[240:241], v[240:241], v[116:117]
	v_cvt_pk_bf16_f32 v125, v240, v241
	v_ashrrev_i32_e32 v153, 31, v152
	v_mov_b64_e32 v[114:115], s[18:19]
	v_mad_i64_i32 v[118:119], s[52:53], v150, s63, v[114:115]
	v_lshlrev_b64 v[116:117], 1, v[152:153]
	v_lshl_add_u64 v[118:119], v[118:119], 0, v[116:117]
	global_store_dwordx4 v[118:119], v[122:125], off
	s_nop 1
	v_pk_mul_f32 v[230:231], v[110:111], s[98:99]
	v_exp_f32_e32 v230, v230
	v_exp_f32_e32 v231, v231
	v_add_f32_e32 v230, 1.0, v230
	v_add_f32_e32 v231, 1.0, v231
	v_rcp_f32_e32 v230, v230
	v_rcp_f32_e32 v231, v231
	v_mul_f32_e32 v234, v110, v230
	v_mul_f32_e32 v235, v111, v231
	v_pk_mul_f32 v[234:235], v[234:235], v[106:107]
	v_cvt_pk_bf16_f32 v106, v234, v235
	v_pk_mul_f32 v[230:231], v[112:113], s[98:99]
	v_exp_f32_e32 v230, v230
	v_exp_f32_e32 v231, v231
	v_add_f32_e32 v230, 1.0, v230
	v_add_f32_e32 v231, 1.0, v231
	v_rcp_f32_e32 v230, v230
	v_rcp_f32_e32 v231, v231
	v_mul_f32_e32 v236, v112, v230
	v_mul_f32_e32 v237, v113, v231
	v_pk_mul_f32 v[236:237], v[236:237], v[108:109]
	v_cvt_pk_bf16_f32 v107, v236, v237
	v_pk_mul_f32 v[230:231], v[102:103], s[98:99]
	v_exp_f32_e32 v230, v230
	v_exp_f32_e32 v231, v231
	v_add_f32_e32 v230, 1.0, v230
	v_add_f32_e32 v231, 1.0, v231
	v_rcp_f32_e32 v230, v230
	v_rcp_f32_e32 v231, v231
	v_mul_f32_e32 v238, v102, v230
	v_mul_f32_e32 v239, v103, v231
	v_pk_mul_f32 v[238:239], v[238:239], v[98:99]
	v_cvt_pk_bf16_f32 v108, v238, v239
	v_pk_mul_f32 v[230:231], v[104:105], s[98:99]
	v_exp_f32_e32 v230, v230
	v_exp_f32_e32 v231, v231
	v_add_f32_e32 v230, 1.0, v230
	v_add_f32_e32 v231, 1.0, v231
	v_rcp_f32_e32 v230, v230
	v_rcp_f32_e32 v231, v231
	v_mul_f32_e32 v240, v104, v230
	v_mul_f32_e32 v241, v105, v231
	v_pk_mul_f32 v[240:241], v[240:241], v[100:101]
	v_cvt_pk_bf16_f32 v109, v240, v241
	v_or_b32_e32 v98, 16, v150
	v_mad_i64_i32 v[98:99], s[52:53], v98, s63, v[114:115]
	v_lshl_add_u64 v[98:99], v[98:99], 0, v[116:117]
	global_store_dwordx4 v[98:99], v[106:109], off
	v_pk_mul_f32 v[230:231], v[94:95], s[98:99]
	v_exp_f32_e32 v230, v230
	v_exp_f32_e32 v231, v231
	v_add_f32_e32 v230, 1.0, v230
	v_add_f32_e32 v231, 1.0, v231
	v_rcp_f32_e32 v230, v230
	v_rcp_f32_e32 v231, v231
	v_mul_f32_e32 v234, v94, v230
	v_mul_f32_e32 v235, v95, v231
	v_pk_mul_f32 v[234:235], v[234:235], v[90:91]
	v_cvt_pk_bf16_f32 v90, v234, v235
	v_pk_mul_f32 v[230:231], v[96:97], s[98:99]
	v_exp_f32_e32 v230, v230
	v_exp_f32_e32 v231, v231
	v_add_f32_e32 v230, 1.0, v230
	v_add_f32_e32 v231, 1.0, v231
	v_rcp_f32_e32 v230, v230
	v_rcp_f32_e32 v231, v231
	v_mul_f32_e32 v236, v96, v230
	v_mul_f32_e32 v237, v97, v231
	v_pk_mul_f32 v[236:237], v[236:237], v[92:93]
	v_cvt_pk_bf16_f32 v91, v236, v237
	v_pk_mul_f32 v[230:231], v[86:87], s[98:99]
	v_exp_f32_e32 v230, v230
	v_exp_f32_e32 v231, v231
	v_add_f32_e32 v230, 1.0, v230
	v_add_f32_e32 v231, 1.0, v231
	v_rcp_f32_e32 v230, v230
	v_rcp_f32_e32 v231, v231
	v_mul_f32_e32 v238, v86, v230
	v_mul_f32_e32 v239, v87, v231
	v_pk_mul_f32 v[238:239], v[238:239], v[82:83]
	v_cvt_pk_bf16_f32 v92, v238, v239
	v_pk_mul_f32 v[230:231], v[88:89], s[98:99]
	v_exp_f32_e32 v230, v230
	v_exp_f32_e32 v231, v231
	v_add_f32_e32 v230, 1.0, v230
	v_add_f32_e32 v231, 1.0, v231
	v_rcp_f32_e32 v230, v230
	v_rcp_f32_e32 v231, v231
	v_mul_f32_e32 v240, v88, v230
	v_mul_f32_e32 v241, v89, v231
	v_pk_mul_f32 v[240:241], v[240:241], v[84:85]
	v_cvt_pk_bf16_f32 v93, v240, v241
	v_or_b32_e32 v82, 32, v150
	v_mad_i64_i32 v[82:83], s[52:53], v82, s63, v[114:115]
	v_lshl_add_u64 v[82:83], v[82:83], 0, v[116:117]
	global_store_dwordx4 v[82:83], v[90:93], off
	v_pk_mul_f32 v[230:231], v[78:79], s[98:99]
	v_exp_f32_e32 v230, v230
	v_exp_f32_e32 v231, v231
	v_add_f32_e32 v230, 1.0, v230
	v_add_f32_e32 v231, 1.0, v231
	v_rcp_f32_e32 v230, v230
	v_rcp_f32_e32 v231, v231
	v_mul_f32_e32 v234, v78, v230
	v_mul_f32_e32 v235, v79, v231
	v_pk_mul_f32 v[234:235], v[234:235], v[74:75]
	v_cvt_pk_bf16_f32 v74, v234, v235
	v_pk_mul_f32 v[230:231], v[80:81], s[98:99]
	v_exp_f32_e32 v230, v230
	v_exp_f32_e32 v231, v231
	v_add_f32_e32 v230, 1.0, v230
	v_add_f32_e32 v231, 1.0, v231
	v_rcp_f32_e32 v230, v230
	v_rcp_f32_e32 v231, v231
	v_mul_f32_e32 v236, v80, v230
	v_mul_f32_e32 v237, v81, v231
	v_pk_mul_f32 v[236:237], v[236:237], v[76:77]
	v_cvt_pk_bf16_f32 v75, v236, v237
	v_pk_mul_f32 v[230:231], v[70:71], s[98:99]
	v_exp_f32_e32 v230, v230
	v_exp_f32_e32 v231, v231
	v_add_f32_e32 v230, 1.0, v230
	v_add_f32_e32 v231, 1.0, v231
	v_rcp_f32_e32 v230, v230
	v_rcp_f32_e32 v231, v231
	v_mul_f32_e32 v238, v70, v230
	v_mul_f32_e32 v239, v71, v231
	v_pk_mul_f32 v[238:239], v[238:239], v[66:67]
	v_cvt_pk_bf16_f32 v76, v238, v239
	v_pk_mul_f32 v[230:231], v[72:73], s[98:99]
	v_exp_f32_e32 v230, v230
	v_exp_f32_e32 v231, v231
	v_add_f32_e32 v230, 1.0, v230
	v_add_f32_e32 v231, 1.0, v231
	v_rcp_f32_e32 v230, v230
	v_rcp_f32_e32 v231, v231
	v_mul_f32_e32 v240, v72, v230
	v_mul_f32_e32 v241, v73, v231
	v_pk_mul_f32 v[240:241], v[240:241], v[68:69]
	v_cvt_pk_bf16_f32 v77, v240, v241
	v_or_b32_e32 v66, 48, v150
	v_mad_i64_i32 v[66:67], s[52:53], v66, s63, v[114:115]
	v_lshl_add_u64 v[66:67], v[66:67], 0, v[116:117]
	global_store_dwordx4 v[66:67], v[74:77], off
	v_pk_mul_f32 v[230:231], v[62:63], s[98:99]
	v_exp_f32_e32 v230, v230
	v_exp_f32_e32 v231, v231
	v_add_f32_e32 v230, 1.0, v230
	v_add_f32_e32 v231, 1.0, v231
	v_rcp_f32_e32 v230, v230
	v_rcp_f32_e32 v231, v231
	v_mul_f32_e32 v234, v62, v230
	v_mul_f32_e32 v235, v63, v231
	v_pk_mul_f32 v[234:235], v[234:235], v[58:59]
	v_cvt_pk_bf16_f32 v58, v234, v235
	v_pk_mul_f32 v[230:231], v[64:65], s[98:99]
	v_exp_f32_e32 v230, v230
	v_exp_f32_e32 v231, v231
	v_add_f32_e32 v230, 1.0, v230
	v_add_f32_e32 v231, 1.0, v231
	v_rcp_f32_e32 v230, v230
	v_rcp_f32_e32 v231, v231
	v_mul_f32_e32 v236, v64, v230
	v_mul_f32_e32 v237, v65, v231
	v_pk_mul_f32 v[236:237], v[236:237], v[60:61]
	v_cvt_pk_bf16_f32 v59, v236, v237
	v_pk_mul_f32 v[230:231], v[54:55], s[98:99]
	v_exp_f32_e32 v230, v230
	v_exp_f32_e32 v231, v231
	v_add_f32_e32 v230, 1.0, v230
	v_add_f32_e32 v231, 1.0, v231
	v_rcp_f32_e32 v230, v230
	v_rcp_f32_e32 v231, v231
	v_mul_f32_e32 v238, v54, v230
	v_mul_f32_e32 v239, v55, v231
	v_pk_mul_f32 v[238:239], v[238:239], v[50:51]
	v_cvt_pk_bf16_f32 v60, v238, v239
	v_pk_mul_f32 v[230:231], v[56:57], s[98:99]
	v_exp_f32_e32 v230, v230
	v_exp_f32_e32 v231, v231
	v_add_f32_e32 v230, 1.0, v230
	v_add_f32_e32 v231, 1.0, v231
	v_rcp_f32_e32 v230, v230
	v_rcp_f32_e32 v231, v231
	v_mul_f32_e32 v240, v56, v230
	v_mul_f32_e32 v241, v57, v231
	v_pk_mul_f32 v[240:241], v[240:241], v[52:53]
	v_add_u32_e32 v66, 0x80, v150
	v_cvt_pk_bf16_f32 v61, v240, v241
	v_mad_i64_i32 v[50:51], s[52:53], v66, s63, v[114:115]
	v_lshl_add_u64 v[50:51], v[50:51], 0, v[116:117]
	global_store_dwordx4 v[50:51], v[58:61], off
	v_pk_mul_f32 v[230:231], v[46:47], s[98:99]
	v_exp_f32_e32 v230, v230
	v_exp_f32_e32 v231, v231
	v_add_f32_e32 v230, 1.0, v230
	v_add_f32_e32 v231, 1.0, v231
	v_rcp_f32_e32 v230, v230
	v_rcp_f32_e32 v231, v231
	v_mul_f32_e32 v234, v46, v230
	v_mul_f32_e32 v235, v47, v231
	v_pk_mul_f32 v[234:235], v[234:235], v[42:43]
	v_cvt_pk_bf16_f32 v42, v234, v235
	v_pk_mul_f32 v[230:231], v[48:49], s[98:99]
	v_exp_f32_e32 v230, v230
	v_exp_f32_e32 v231, v231
	v_add_f32_e32 v230, 1.0, v230
	v_add_f32_e32 v231, 1.0, v231
	v_rcp_f32_e32 v230, v230
	v_rcp_f32_e32 v231, v231
	v_mul_f32_e32 v236, v48, v230
	v_mul_f32_e32 v237, v49, v231
	v_pk_mul_f32 v[236:237], v[236:237], v[44:45]
	v_cvt_pk_bf16_f32 v43, v236, v237
	v_pk_mul_f32 v[230:231], v[38:39], s[98:99]
	v_exp_f32_e32 v230, v230
	v_exp_f32_e32 v231, v231
	v_add_f32_e32 v230, 1.0, v230
	v_add_f32_e32 v231, 1.0, v231
	v_rcp_f32_e32 v230, v230
	v_rcp_f32_e32 v231, v231
	v_mul_f32_e32 v238, v38, v230
	v_mul_f32_e32 v239, v39, v231
	v_pk_mul_f32 v[238:239], v[238:239], v[34:35]
	v_cvt_pk_bf16_f32 v44, v238, v239
	v_pk_mul_f32 v[230:231], v[40:41], s[98:99]
	v_exp_f32_e32 v230, v230
	v_exp_f32_e32 v231, v231
	v_add_f32_e32 v230, 1.0, v230
	v_add_f32_e32 v231, 1.0, v231
	v_rcp_f32_e32 v230, v230
	v_rcp_f32_e32 v231, v231
	v_mul_f32_e32 v240, v40, v230
	v_mul_f32_e32 v241, v41, v231
	v_pk_mul_f32 v[240:241], v[240:241], v[36:37]
	v_cvt_pk_bf16_f32 v45, v240, v241
	v_add_u32_e32 v34, 0x90, v150
	v_mad_i64_i32 v[34:35], s[52:53], v34, s63, v[114:115]
	v_lshl_add_u64 v[34:35], v[34:35], 0, v[116:117]
	global_store_dwordx4 v[34:35], v[42:45], off
	v_pk_mul_f32 v[230:231], v[30:31], s[98:99]
	v_exp_f32_e32 v230, v230
	v_exp_f32_e32 v231, v231
	v_add_f32_e32 v230, 1.0, v230
	v_add_f32_e32 v231, 1.0, v231
	v_rcp_f32_e32 v230, v230
	v_rcp_f32_e32 v231, v231
	v_mul_f32_e32 v234, v30, v230
	v_mul_f32_e32 v235, v31, v231
	v_pk_mul_f32 v[234:235], v[234:235], v[26:27]
	v_cvt_pk_bf16_f32 v26, v234, v235
	v_pk_mul_f32 v[230:231], v[32:33], s[98:99]
	v_exp_f32_e32 v230, v230
	v_exp_f32_e32 v231, v231
	v_add_f32_e32 v230, 1.0, v230
	v_add_f32_e32 v231, 1.0, v231
	v_rcp_f32_e32 v230, v230
	v_rcp_f32_e32 v231, v231
	v_mul_f32_e32 v236, v32, v230
	v_mul_f32_e32 v237, v33, v231
	v_pk_mul_f32 v[236:237], v[236:237], v[28:29]
	v_cvt_pk_bf16_f32 v27, v236, v237
	v_pk_mul_f32 v[230:231], v[22:23], s[98:99]
	v_exp_f32_e32 v230, v230
	v_exp_f32_e32 v231, v231
	v_add_f32_e32 v230, 1.0, v230
	v_add_f32_e32 v231, 1.0, v231
	v_rcp_f32_e32 v230, v230
	v_rcp_f32_e32 v231, v231
	v_mul_f32_e32 v238, v22, v230
	v_mul_f32_e32 v239, v23, v231
	v_pk_mul_f32 v[238:239], v[238:239], v[18:19]
	v_cvt_pk_bf16_f32 v28, v238, v239
	v_pk_mul_f32 v[230:231], v[24:25], s[98:99]
	v_exp_f32_e32 v230, v230
	v_exp_f32_e32 v231, v231
	v_add_f32_e32 v230, 1.0, v230
	v_add_f32_e32 v231, 1.0, v231
	v_rcp_f32_e32 v230, v230
	v_rcp_f32_e32 v231, v231
	v_mul_f32_e32 v240, v24, v230
	v_mul_f32_e32 v241, v25, v231
	v_pk_mul_f32 v[240:241], v[240:241], v[20:21]
	v_cvt_pk_bf16_f32 v29, v240, v241
	v_add_u32_e32 v18, 0xa0, v150
	v_mad_i64_i32 v[18:19], s[52:53], v18, s63, v[114:115]
	v_lshl_add_u64 v[18:19], v[18:19], 0, v[116:117]
	global_store_dwordx4 v[18:19], v[26:29], off
	v_pk_mul_f32 v[230:231], v[14:15], s[98:99]
	v_exp_f32_e32 v230, v230
	v_exp_f32_e32 v231, v231
	v_add_f32_e32 v230, 1.0, v230
	v_add_f32_e32 v231, 1.0, v231
	v_rcp_f32_e32 v230, v230
	v_rcp_f32_e32 v231, v231
	v_mul_f32_e32 v234, v14, v230
	v_mul_f32_e32 v235, v15, v231
	v_pk_mul_f32 v[234:235], v[234:235], v[10:11]
	v_cvt_pk_bf16_f32 v10, v234, v235
	v_pk_mul_f32 v[230:231], v[16:17], s[98:99]
	v_exp_f32_e32 v230, v230
	v_exp_f32_e32 v231, v231
	v_add_f32_e32 v230, 1.0, v230
	v_add_f32_e32 v231, 1.0, v231
	v_rcp_f32_e32 v230, v230
	v_rcp_f32_e32 v231, v231
	v_mul_f32_e32 v236, v16, v230
	v_mul_f32_e32 v237, v17, v231
	v_pk_mul_f32 v[236:237], v[236:237], v[12:13]
	v_cvt_pk_bf16_f32 v11, v236, v237
	v_pk_mul_f32 v[230:231], v[6:7], s[98:99]
	v_exp_f32_e32 v230, v230
	v_exp_f32_e32 v231, v231
	v_add_f32_e32 v230, 1.0, v230
	v_add_f32_e32 v231, 1.0, v231
	v_rcp_f32_e32 v230, v230
	v_rcp_f32_e32 v231, v231
	v_mul_f32_e32 v238, v6, v230
	v_mul_f32_e32 v239, v7, v231
	v_pk_mul_f32 v[238:239], v[238:239], v[2:3]
	v_cvt_pk_bf16_f32 v12, v238, v239
	v_pk_mul_f32 v[230:231], v[8:9], s[98:99]
	v_exp_f32_e32 v230, v230
	v_exp_f32_e32 v231, v231
	v_add_f32_e32 v230, 1.0, v230
	v_add_f32_e32 v231, 1.0, v231
	v_rcp_f32_e32 v230, v230
	v_rcp_f32_e32 v231, v231
	v_mul_f32_e32 v240, v8, v230
	v_mul_f32_e32 v241, v9, v231
	v_pk_mul_f32 v[240:241], v[240:241], v[4:5]
	v_cvt_pk_bf16_f32 v13, v240, v241
	v_add_u32_e32 v2, 0xb0, v150
	v_mad_i64_i32 v[2:3], s[52:53], v2, s63, v[114:115]
	v_lshl_add_u64 v[2:3], v[2:3], 0, v[116:117]
	s_mov_b64 s[52:53], -1
	s_and_b64 vcc, exec, s[48:49]
	global_store_dwordx4 v[2:3], v[10:13], off
	s_cbranch_vccz .LBB0_3459
	s_andn2_b64 vcc, exec, s[6:7]
	s_cbranch_vccnz .LBB0_3458
	s_nop 0
	s_branch .LBB0_3458

.LBB0_5819:
	ds_read_b128 v[148:151], v143
	ds_read_b128 v[152:155], v143 offset:1024
	ds_read_b128 v[156:159], v143 offset:2048
	ds_read_b128 v[160:163], v143 offset:3072
	ds_read_b128 v[164:167], v144
	ds_read_b128 v[168:171], v144 offset:1024
	ds_read_b128 v[172:175], v144 offset:2048
	ds_read_b128 v[176:179], v144 offset:3072
	s_add_u32 s46, s44, 0xfffc0080
	s_addc_u32 s47, s45, -1
	s_cmp_eq_u32 s64, 12
	s_cselect_b32 s49, s25, s47
	s_cselect_b32 s48, s60, s46
	s_cselect_b32 s47, s23, s63
	s_cselect_b32 s46, s61, s62
	v_lshl_add_u64 v[212:213], s[44:45], 0, v[140:141]
	s_add_i32 m0, s35, 0xc000
	ds_read_b128 v[180:183], v145
	ds_read_b128 v[184:187], v145 offset:1024
	ds_read_b128 v[188:191], v145 offset:2048
	ds_read_b128 v[192:195], v145 offset:3072
	ds_read_b128 v[196:199], v145 offset:4096
	ds_read_b128 v[200:203], v145 offset:5120
	ds_read_b128 v[204:207], v145 offset:6144
	ds_read_b128 v[208:211], v145 offset:7168
	global_load_lds_dwordx4 v[212:213], off
	v_lshl_add_u64 v[212:213], s[44:45], 0, v[138:139]
	s_add_i32 m0, s35, 0xe000
	s_nop 0
	global_load_lds_dwordx4 v[212:213], off
	s_waitcnt vmcnt(8)
	s_waitcnt lgkmcnt(0)
	s_barrier
	s_setprio 1
	s_waitcnt lgkmcnt(0)
	v_mfma_f32_16x16x32_bf16 v[126:129], v[148:151], v[180:183], v[126:129]
	v_mfma_f32_16x16x32_bf16 v[118:121], v[156:159], v[180:183], v[118:121]
	v_mfma_f32_16x16x32_bf16 v[110:113], v[148:151], v[188:191], v[110:113]
	v_mfma_f32_16x16x32_bf16 v[102:105], v[156:159], v[188:191], v[102:105]
	v_mfma_f32_16x16x32_bf16 v[94:97], v[148:151], v[196:199], v[94:97]
	v_mfma_f32_16x16x32_bf16 v[86:89], v[156:159], v[196:199], v[86:89]
	v_mfma_f32_16x16x32_bf16 v[78:81], v[148:151], v[204:207], v[78:81]
	v_mfma_f32_16x16x32_bf16 v[70:73], v[156:159], v[204:207], v[70:73]
	v_mfma_f32_16x16x32_bf16 v[126:129], v[152:155], v[184:187], v[126:129]
	v_mfma_f32_16x16x32_bf16 v[118:121], v[160:163], v[184:187], v[118:121]
	v_mfma_f32_16x16x32_bf16 v[110:113], v[152:155], v[192:195], v[110:113]
	v_mfma_f32_16x16x32_bf16 v[102:105], v[160:163], v[192:195], v[102:105]
	v_mfma_f32_16x16x32_bf16 v[94:97], v[152:155], v[200:203], v[94:97]
	v_mfma_f32_16x16x32_bf16 v[86:89], v[160:163], v[200:203], v[86:89]
	v_mfma_f32_16x16x32_bf16 v[78:81], v[152:155], v[208:211], v[78:81]
	v_mfma_f32_16x16x32_bf16 v[70:73], v[160:163], v[208:211], v[70:73]
	s_setprio 0
	s_setprio 1
	v_mfma_f32_16x16x32_bf16 v[122:125], v[164:167], v[180:183], v[122:125]
	v_mfma_f32_16x16x32_bf16 v[114:117], v[172:175], v[180:183], v[114:117]
	v_mfma_f32_16x16x32_bf16 v[106:109], v[164:167], v[188:191], v[106:109]
	v_mfma_f32_16x16x32_bf16 v[98:101], v[172:175], v[188:191], v[98:101]
	v_mfma_f32_16x16x32_bf16 v[90:93], v[164:167], v[196:199], v[90:93]
	v_mfma_f32_16x16x32_bf16 v[82:85], v[172:175], v[196:199], v[82:85]
	v_mfma_f32_16x16x32_bf16 v[74:77], v[164:167], v[204:207], v[74:77]
	v_mfma_f32_16x16x32_bf16 v[66:69], v[172:175], v[204:207], v[66:69]
	v_mfma_f32_16x16x32_bf16 v[122:125], v[168:171], v[184:187], v[122:125]
	v_mfma_f32_16x16x32_bf16 v[114:117], v[176:179], v[184:187], v[114:117]
	v_mfma_f32_16x16x32_bf16 v[106:109], v[168:171], v[192:195], v[106:109]
	v_mfma_f32_16x16x32_bf16 v[98:101], v[176:179], v[192:195], v[98:101]
	v_mfma_f32_16x16x32_bf16 v[90:93], v[168:171], v[200:203], v[90:93]
	v_mfma_f32_16x16x32_bf16 v[82:85], v[176:179], v[200:203], v[82:85]
	v_mfma_f32_16x16x32_bf16 v[74:77], v[168:171], v[208:211], v[74:77]
	v_mfma_f32_16x16x32_bf16 v[66:69], v[176:179], v[208:211], v[66:69]
	s_setprio 0
	s_barrier
	s_mov_b32 m0, s30
	v_lshl_add_u64 v[212:213], s[46:47], 0, v[132:133]
	s_add_u32 s66, s46, 0x40000
	ds_read_b128 v[180:183], v145 offset:16384
	ds_read_b128 v[184:187], v145 offset:17408
	ds_read_b128 v[188:191], v145 offset:18432
	ds_read_b128 v[192:195], v145 offset:19456
	ds_read_b128 v[196:199], v145 offset:20480
	ds_read_b128 v[200:203], v145 offset:21504
	ds_read_b128 v[204:207], v145 offset:22528
	ds_read_b128 v[208:211], v145 offset:23552
	global_load_lds_dwordx4 v[212:213], off
	v_lshl_add_u64 v[214:215], s[46:47], 0, v[136:137]
	s_mov_b32 m0, s31
	s_addc_u32 s67, s47, 0
	global_load_lds_dwordx4 v[214:215], off
	v_lshl_add_u64 v[216:217], s[66:67], 0, v[132:133]
	s_mov_b32 m0, s33
	v_lshl_add_u64 v[218:219], s[48:49], 0, v[134:135]
	global_load_lds_dwordx4 v[216:217], off
	v_lshl_add_u64 v[216:217], s[66:67], 0, v[136:137]
	s_mov_b32 m0, s34
	s_nop 0
	global_load_lds_dwordx4 v[216:217], off
	v_lshl_add_u64 v[216:217], s[48:49], 0, v[130:131]
	s_mov_b32 m0, s35
	s_nop 0
	global_load_lds_dwordx4 v[216:217], off
	s_mov_b32 m0, s36
	s_nop 0
	global_load_lds_dwordx4 v[218:219], off
	s_waitcnt vmcnt(8)
	s_waitcnt lgkmcnt(0)
	s_barrier
	s_setprio 1
	s_waitcnt lgkmcnt(0)
	v_mfma_f32_16x16x32_bf16 v[62:65], v[148:151], v[180:183], v[62:65]
	v_mfma_f32_16x16x32_bf16 v[54:57], v[156:159], v[180:183], v[54:57]
	v_mfma_f32_16x16x32_bf16 v[46:49], v[148:151], v[188:191], v[46:49]
	v_mfma_f32_16x16x32_bf16 v[38:41], v[156:159], v[188:191], v[38:41]
	v_mfma_f32_16x16x32_bf16 v[30:33], v[148:151], v[196:199], v[30:33]
	v_mfma_f32_16x16x32_bf16 v[22:25], v[156:159], v[196:199], v[22:25]
	v_mfma_f32_16x16x32_bf16 v[14:17], v[148:151], v[204:207], v[14:17]
	v_mfma_f32_16x16x32_bf16 v[6:9], v[156:159], v[204:207], v[6:9]
	v_mfma_f32_16x16x32_bf16 v[62:65], v[152:155], v[184:187], v[62:65]
	v_mfma_f32_16x16x32_bf16 v[54:57], v[160:163], v[184:187], v[54:57]
	v_mfma_f32_16x16x32_bf16 v[46:49], v[152:155], v[192:195], v[46:49]
	v_mfma_f32_16x16x32_bf16 v[38:41], v[160:163], v[192:195], v[38:41]
	v_mfma_f32_16x16x32_bf16 v[30:33], v[152:155], v[200:203], v[30:33]
	v_mfma_f32_16x16x32_bf16 v[22:25], v[160:163], v[200:203], v[22:25]
	v_mfma_f32_16x16x32_bf16 v[14:17], v[152:155], v[208:211], v[14:17]
	v_mfma_f32_16x16x32_bf16 v[6:9], v[160:163], v[208:211], v[6:9]
	s_setprio 0
	s_setprio 1
	v_mfma_f32_16x16x32_bf16 v[58:61], v[164:167], v[180:183], v[58:61]
	v_mfma_f32_16x16x32_bf16 v[50:53], v[172:175], v[180:183], v[50:53]
	v_mfma_f32_16x16x32_bf16 v[42:45], v[164:167], v[188:191], v[42:45]
	v_mfma_f32_16x16x32_bf16 v[34:37], v[172:175], v[188:191], v[34:37]
	v_mfma_f32_16x16x32_bf16 v[26:29], v[164:167], v[196:199], v[26:29]
	v_mfma_f32_16x16x32_bf16 v[18:21], v[172:175], v[196:199], v[18:21]
	v_mfma_f32_16x16x32_bf16 v[10:13], v[164:167], v[204:207], v[10:13]
	v_mfma_f32_16x16x32_bf16 v[2:5], v[172:175], v[204:207], v[2:5]
	v_mfma_f32_16x16x32_bf16 v[58:61], v[168:171], v[184:187], v[58:61]
	v_mfma_f32_16x16x32_bf16 v[50:53], v[176:179], v[184:187], v[50:53]
	v_mfma_f32_16x16x32_bf16 v[42:45], v[168:171], v[192:195], v[42:45]
	v_mfma_f32_16x16x32_bf16 v[34:37], v[176:179], v[192:195], v[34:37]
	v_mfma_f32_16x16x32_bf16 v[26:29], v[168:171], v[200:203], v[26:29]
	v_mfma_f32_16x16x32_bf16 v[18:21], v[176:179], v[200:203], v[18:21]
	v_mfma_f32_16x16x32_bf16 v[10:13], v[168:171], v[208:211], v[10:13]
	v_mfma_f32_16x16x32_bf16 v[2:5], v[176:179], v[208:211], v[2:5]
	s_setprio 0
	s_barrier
	ds_read_b128 v[148:151], v146
	ds_read_b128 v[152:155], v146 offset:1024
	ds_read_b128 v[156:159], v146 offset:2048
	ds_read_b128 v[160:163], v146 offset:3072
	ds_read_b128 v[164:167], v147
	ds_read_b128 v[168:171], v147 offset:1024
	ds_read_b128 v[172:175], v147 offset:2048
	ds_read_b128 v[176:179], v147 offset:3072
	s_add_u32 s48, s48, 0x40000
	s_addc_u32 s49, s49, 0
	s_mov_b32 m0, s37
	v_lshl_add_u64 v[220:221], s[48:49], 0, v[130:131]
	ds_read_b128 v[180:183], v145 offset:32768
	ds_read_b128 v[184:187], v145 offset:33792
	ds_read_b128 v[188:191], v145 offset:34816
	ds_read_b128 v[192:195], v145 offset:35840
	ds_read_b128 v[196:199], v145 offset:36864
	ds_read_b128 v[200:203], v145 offset:37888
	ds_read_b128 v[204:207], v145 offset:38912
	ds_read_b128 v[208:211], v145 offset:39936
	global_load_lds_dwordx4 v[220:221], off
	v_lshl_add_u64 v[220:221], s[48:49], 0, v[134:135]
	s_mov_b32 m0, s50
	s_nop 0
	global_load_lds_dwordx4 v[220:221], off
	s_waitcnt vmcnt(8)
	s_waitcnt lgkmcnt(0)
	s_barrier
	s_setprio 1
	s_waitcnt lgkmcnt(0)
	v_mfma_f32_16x16x32_bf16 v[126:129], v[148:151], v[180:183], v[126:129]
	v_mfma_f32_16x16x32_bf16 v[118:121], v[156:159], v[180:183], v[118:121]
	v_mfma_f32_16x16x32_bf16 v[110:113], v[148:151], v[188:191], v[110:113]
	v_mfma_f32_16x16x32_bf16 v[102:105], v[156:159], v[188:191], v[102:105]
	v_mfma_f32_16x16x32_bf16 v[94:97], v[148:151], v[196:199], v[94:97]
	v_mfma_f32_16x16x32_bf16 v[86:89], v[156:159], v[196:199], v[86:89]
	v_mfma_f32_16x16x32_bf16 v[78:81], v[148:151], v[204:207], v[78:81]
	v_mfma_f32_16x16x32_bf16 v[70:73], v[156:159], v[204:207], v[70:73]
	v_mfma_f32_16x16x32_bf16 v[126:129], v[152:155], v[184:187], v[126:129]
	v_mfma_f32_16x16x32_bf16 v[118:121], v[160:163], v[184:187], v[118:121]
	v_mfma_f32_16x16x32_bf16 v[110:113], v[152:155], v[192:195], v[110:113]
	v_mfma_f32_16x16x32_bf16 v[102:105], v[160:163], v[192:195], v[102:105]
	v_mfma_f32_16x16x32_bf16 v[94:97], v[152:155], v[200:203], v[94:97]
	v_mfma_f32_16x16x32_bf16 v[86:89], v[160:163], v[200:203], v[86:89]
	v_mfma_f32_16x16x32_bf16 v[78:81], v[152:155], v[208:211], v[78:81]
	v_mfma_f32_16x16x32_bf16 v[70:73], v[160:163], v[208:211], v[70:73]
	s_setprio 0
	s_setprio 1
	v_mfma_f32_16x16x32_bf16 v[122:125], v[164:167], v[180:183], v[122:125]
	v_mfma_f32_16x16x32_bf16 v[114:117], v[172:175], v[180:183], v[114:117]
	v_mfma_f32_16x16x32_bf16 v[106:109], v[164:167], v[188:191], v[106:109]
	v_mfma_f32_16x16x32_bf16 v[98:101], v[172:175], v[188:191], v[98:101]
	v_mfma_f32_16x16x32_bf16 v[90:93], v[164:167], v[196:199], v[90:93]
	v_mfma_f32_16x16x32_bf16 v[82:85], v[172:175], v[196:199], v[82:85]
	v_mfma_f32_16x16x32_bf16 v[74:77], v[164:167], v[204:207], v[74:77]
	v_mfma_f32_16x16x32_bf16 v[66:69], v[172:175], v[204:207], v[66:69]
	v_mfma_f32_16x16x32_bf16 v[122:125], v[168:171], v[184:187], v[122:125]
	v_mfma_f32_16x16x32_bf16 v[114:117], v[176:179], v[184:187], v[114:117]
	v_mfma_f32_16x16x32_bf16 v[106:109], v[168:171], v[192:195], v[106:109]
	v_mfma_f32_16x16x32_bf16 v[98:101], v[176:179], v[192:195], v[98:101]
	v_mfma_f32_16x16x32_bf16 v[90:93], v[168:171], v[200:203], v[90:93]
	v_mfma_f32_16x16x32_bf16 v[82:85], v[176:179], v[200:203], v[82:85]
	v_mfma_f32_16x16x32_bf16 v[74:77], v[168:171], v[208:211], v[74:77]
	v_mfma_f32_16x16x32_bf16 v[66:69], v[176:179], v[208:211], v[66:69]
	s_setprio 0
	s_barrier
	s_mov_b32 m0, s52
	v_lshl_add_u64 v[212:213], v[212:213], 0, s[8:9]
	s_add_u32 s46, s46, 0x40080
	ds_read_b128 v[180:183], v145 offset:49152
	ds_read_b128 v[184:187], v145 offset:50176
	ds_read_b128 v[188:191], v145 offset:51200
	ds_read_b128 v[192:195], v145 offset:52224
	ds_read_b128 v[196:199], v145 offset:53248
	ds_read_b128 v[200:203], v145 offset:54272
	ds_read_b128 v[204:207], v145 offset:55296
	ds_read_b128 v[208:211], v145 offset:56320
	global_load_lds_dwordx4 v[212:213], off
	v_lshl_add_u64 v[212:213], v[214:215], 0, s[8:9]
	s_mov_b32 m0, s53
	s_addc_u32 s47, s47, 0
	global_load_lds_dwordx4 v[212:213], off
	v_lshl_add_u64 v[212:213], s[46:47], 0, v[132:133]
	s_mov_b32 m0, s56
	s_nop 0
	global_load_lds_dwordx4 v[212:213], off
	v_lshl_add_u64 v[212:213], s[46:47], 0, v[136:137]
	s_mov_b32 m0, s57
	s_nop 0
	global_load_lds_dwordx4 v[212:213], off
	v_lshl_add_u64 v[212:213], v[216:217], 0, s[8:9]
	s_mov_b32 m0, s54
	s_nop 0
	global_load_lds_dwordx4 v[212:213], off
	v_lshl_add_u64 v[212:213], v[218:219], 0, s[8:9]
	s_mov_b32 m0, s55
	s_nop 0
	global_load_lds_dwordx4 v[212:213], off
	s_waitcnt vmcnt(8)
	s_waitcnt lgkmcnt(0)
	s_barrier
	s_setprio 1
	s_waitcnt lgkmcnt(0)
	v_mfma_f32_16x16x32_bf16 v[62:65], v[148:151], v[180:183], v[62:65]
	v_mfma_f32_16x16x32_bf16 v[54:57], v[156:159], v[180:183], v[54:57]
	v_mfma_f32_16x16x32_bf16 v[46:49], v[148:151], v[188:191], v[46:49]
	v_mfma_f32_16x16x32_bf16 v[38:41], v[156:159], v[188:191], v[38:41]
	v_mfma_f32_16x16x32_bf16 v[30:33], v[148:151], v[196:199], v[30:33]
	v_mfma_f32_16x16x32_bf16 v[22:25], v[156:159], v[196:199], v[22:25]
	v_mfma_f32_16x16x32_bf16 v[14:17], v[148:151], v[204:207], v[14:17]
	v_mfma_f32_16x16x32_bf16 v[6:9], v[156:159], v[204:207], v[6:9]
	v_mfma_f32_16x16x32_bf16 v[62:65], v[152:155], v[184:187], v[62:65]
	v_mfma_f32_16x16x32_bf16 v[54:57], v[160:163], v[184:187], v[54:57]
	v_mfma_f32_16x16x32_bf16 v[46:49], v[152:155], v[192:195], v[46:49]
	v_mfma_f32_16x16x32_bf16 v[38:41], v[160:163], v[192:195], v[38:41]
	v_mfma_f32_16x16x32_bf16 v[30:33], v[152:155], v[200:203], v[30:33]
	v_mfma_f32_16x16x32_bf16 v[22:25], v[160:163], v[200:203], v[22:25]
	v_mfma_f32_16x16x32_bf16 v[14:17], v[152:155], v[208:211], v[14:17]
	v_mfma_f32_16x16x32_bf16 v[6:9], v[160:163], v[208:211], v[6:9]
	s_setprio 0
	s_setprio 1
	v_mfma_f32_16x16x32_bf16 v[58:61], v[164:167], v[180:183], v[58:61]
	v_mfma_f32_16x16x32_bf16 v[50:53], v[172:175], v[180:183], v[50:53]
	v_mfma_f32_16x16x32_bf16 v[42:45], v[164:167], v[188:191], v[42:45]
	v_mfma_f32_16x16x32_bf16 v[34:37], v[172:175], v[188:191], v[34:37]
	v_mfma_f32_16x16x32_bf16 v[26:29], v[164:167], v[196:199], v[26:29]
	v_mfma_f32_16x16x32_bf16 v[18:21], v[172:175], v[196:199], v[18:21]
	v_mfma_f32_16x16x32_bf16 v[10:13], v[164:167], v[204:207], v[10:13]
	v_mfma_f32_16x16x32_bf16 v[2:5], v[172:175], v[204:207], v[2:5]
	v_mfma_f32_16x16x32_bf16 v[58:61], v[168:171], v[184:187], v[58:61]
	v_mfma_f32_16x16x32_bf16 v[50:53], v[176:179], v[184:187], v[50:53]
	v_mfma_f32_16x16x32_bf16 v[42:45], v[168:171], v[192:195], v[42:45]
	v_mfma_f32_16x16x32_bf16 v[34:37], v[176:179], v[192:195], v[34:37]
	v_mfma_f32_16x16x32_bf16 v[26:29], v[168:171], v[200:203], v[26:29]
	v_mfma_f32_16x16x32_bf16 v[18:21], v[176:179], v[200:203], v[18:21]
	v_mfma_f32_16x16x32_bf16 v[10:13], v[168:171], v[208:211], v[10:13]
	v_mfma_f32_16x16x32_bf16 v[2:5], v[176:179], v[208:211], v[2:5]
	s_setprio 0
	s_barrier
	s_add_i32 s64, s64, 2
	s_add_u32 s62, s62, 0x100
	s_addc_u32 s63, s63, 0
	s_add_u32 s44, s44, 0x100
	s_addc_u32 s45, s45, 0
	s_cmp_lt_u32 s64, 14
	s_cbranch_scc1 .LBB0_5819
	s_orn2_b64 vcc, s[38:39], s[10:11]
	s_and_b64 vcc, exec, vcc
	s_cbranch_vccnz .LBB0_5822
	s_barrier
.LBB0_5822:
	s_mov_b32 s98, 0xbfb8aa3b
	s_mov_b32 s99, 0xbfb8aa3b
	v_lshl_add_u32 v148, s42, 8, v1
	v_lshl_or_b32 v150, s43, 7, v142
	v_pk_mul_f32 v[230:231], v[126:127], s[98:99]
	v_exp_f32_e32 v230, v230
	v_exp_f32_e32 v231, v231
	v_add_f32_e32 v230, 1.0, v230
	v_add_f32_e32 v231, 1.0, v231
	v_rcp_f32_e32 v230, v230
	v_rcp_f32_e32 v231, v231
	v_mul_f32_e32 v234, v126, v230
	v_mul_f32_e32 v235, v127, v231
	v_pk_mul_f32 v[234:235], v[234:235], v[122:123]
	v_cvt_pk_bf16_f32 v122, v234, v235
	v_pk_mul_f32 v[230:231], v[128:129], s[98:99]
	v_exp_f32_e32 v230, v230
	v_exp_f32_e32 v231, v231
	v_add_f32_e32 v230, 1.0, v230
	v_add_f32_e32 v231, 1.0, v231
	v_rcp_f32_e32 v230, v230
	v_rcp_f32_e32 v231, v231
	v_mul_f32_e32 v236, v128, v230
	v_mul_f32_e32 v237, v129, v231
	v_pk_mul_f32 v[236:237], v[236:237], v[124:125]
	v_cvt_pk_bf16_f32 v123, v236, v237
	v_pk_mul_f32 v[230:231], v[118:119], s[98:99]
	v_exp_f32_e32 v230, v230
	v_exp_f32_e32 v231, v231
	v_add_f32_e32 v230, 1.0, v230
	v_add_f32_e32 v231, 1.0, v231
	v_rcp_f32_e32 v230, v230
	v_rcp_f32_e32 v231, v231
	v_mul_f32_e32 v238, v118, v230
	v_mul_f32_e32 v239, v119, v231
	v_pk_mul_f32 v[238:239], v[238:239], v[114:115]
	v_cvt_pk_bf16_f32 v124, v238, v239
	v_pk_mul_f32 v[230:231], v[120:121], s[98:99]
	v_exp_f32_e32 v230, v230
	v_exp_f32_e32 v231, v231
	v_add_f32_e32 v230, 1.0, v230
	v_add_f32_e32 v231, 1.0, v231
	v_rcp_f32_e32 v230, v230
	v_rcp_f32_e32 v231, v231
	v_mul_f32_e32 v240, v120, v230
	v_mul_f32_e32 v241, v121, v231
	v_pk_mul_f32 v[240:241], v[240:241], v[116:117]
	v_cvt_pk_bf16_f32 v125, v240, v241
	v_ashrrev_i32_e32 v151, 31, v150
	v_mov_b64_e32 v[114:115], s[18:19]
	v_mad_i64_i32 v[118:119], s[42:43], v148, s59, v[114:115]
	v_lshlrev_b64 v[116:117], 1, v[150:151]
	v_lshl_add_u64 v[118:119], v[118:119], 0, v[116:117]
	global_store_dwordx4 v[118:119], v[122:125], off
	s_nop 1
	v_pk_mul_f32 v[230:231], v[110:111], s[98:99]
	v_exp_f32_e32 v230, v230
	v_exp_f32_e32 v231, v231
	v_add_f32_e32 v230, 1.0, v230
	v_add_f32_e32 v231, 1.0, v231
	v_rcp_f32_e32 v230, v230
	v_rcp_f32_e32 v231, v231
	v_mul_f32_e32 v234, v110, v230
	v_mul_f32_e32 v235, v111, v231
	v_pk_mul_f32 v[234:235], v[234:235], v[106:107]
	v_cvt_pk_bf16_f32 v106, v234, v235
	v_pk_mul_f32 v[230:231], v[112:113], s[98:99]
	v_exp_f32_e32 v230, v230
	v_exp_f32_e32 v231, v231
	v_add_f32_e32 v230, 1.0, v230
	v_add_f32_e32 v231, 1.0, v231
	v_rcp_f32_e32 v230, v230
	v_rcp_f32_e32 v231, v231
	v_mul_f32_e32 v236, v112, v230
	v_mul_f32_e32 v237, v113, v231
	v_pk_mul_f32 v[236:237], v[236:237], v[108:109]
	v_cvt_pk_bf16_f32 v107, v236, v237
	v_pk_mul_f32 v[230:231], v[102:103], s[98:99]
	v_exp_f32_e32 v230, v230
	v_exp_f32_e32 v231, v231
	v_add_f32_e32 v230, 1.0, v230
	v_add_f32_e32 v231, 1.0, v231
	v_rcp_f32_e32 v230, v230
	v_rcp_f32_e32 v231, v231
	v_mul_f32_e32 v238, v102, v230
	v_mul_f32_e32 v239, v103, v231
	v_pk_mul_f32 v[238:239], v[238:239], v[98:99]
	v_cvt_pk_bf16_f32 v108, v238, v239
	v_pk_mul_f32 v[230:231], v[104:105], s[98:99]
	v_exp_f32_e32 v230, v230
	v_exp_f32_e32 v231, v231
	v_add_f32_e32 v230, 1.0, v230
	v_add_f32_e32 v231, 1.0, v231
	v_rcp_f32_e32 v230, v230
	v_rcp_f32_e32 v231, v231
	v_mul_f32_e32 v240, v104, v230
	v_mul_f32_e32 v241, v105, v231
	v_pk_mul_f32 v[240:241], v[240:241], v[100:101]
	v_cvt_pk_bf16_f32 v109, v240, v241
	v_or_b32_e32 v98, 16, v148
	v_mad_i64_i32 v[98:99], s[42:43], v98, s59, v[114:115]
	v_lshl_add_u64 v[98:99], v[98:99], 0, v[116:117]
	global_store_dwordx4 v[98:99], v[106:109], off
	v_pk_mul_f32 v[230:231], v[94:95], s[98:99]
	v_exp_f32_e32 v230, v230
	v_exp_f32_e32 v231, v231
	v_add_f32_e32 v230, 1.0, v230
	v_add_f32_e32 v231, 1.0, v231
	v_rcp_f32_e32 v230, v230
	v_rcp_f32_e32 v231, v231
	v_mul_f32_e32 v234, v94, v230
	v_mul_f32_e32 v235, v95, v231
	v_pk_mul_f32 v[234:235], v[234:235], v[90:91]
	v_cvt_pk_bf16_f32 v90, v234, v235
	v_pk_mul_f32 v[230:231], v[96:97], s[98:99]
	v_exp_f32_e32 v230, v230
	v_exp_f32_e32 v231, v231
	v_add_f32_e32 v230, 1.0, v230
	v_add_f32_e32 v231, 1.0, v231
	v_rcp_f32_e32 v230, v230
	v_rcp_f32_e32 v231, v231
	v_mul_f32_e32 v236, v96, v230
	v_mul_f32_e32 v237, v97, v231
	v_pk_mul_f32 v[236:237], v[236:237], v[92:93]
	v_cvt_pk_bf16_f32 v91, v236, v237
	v_pk_mul_f32 v[230:231], v[86:87], s[98:99]
	v_exp_f32_e32 v230, v230
	v_exp_f32_e32 v231, v231
	v_add_f32_e32 v230, 1.0, v230
	v_add_f32_e32 v231, 1.0, v231
	v_rcp_f32_e32 v230, v230
	v_rcp_f32_e32 v231, v231
	v_mul_f32_e32 v238, v86, v230
	v_mul_f32_e32 v239, v87, v231
	v_pk_mul_f32 v[238:239], v[238:239], v[82:83]
	v_cvt_pk_bf16_f32 v92, v238, v239
	v_pk_mul_f32 v[230:231], v[88:89], s[98:99]
	v_exp_f32_e32 v230, v230
	v_exp_f32_e32 v231, v231
	v_add_f32_e32 v230, 1.0, v230
	v_add_f32_e32 v231, 1.0, v231
	v_rcp_f32_e32 v230, v230
	v_rcp_f32_e32 v231, v231
	v_mul_f32_e32 v240, v88, v230
	v_mul_f32_e32 v241, v89, v231
	v_pk_mul_f32 v[240:241], v[240:241], v[84:85]
	v_cvt_pk_bf16_f32 v93, v240, v241
	v_or_b32_e32 v82, 32, v148
	v_mad_i64_i32 v[82:83], s[42:43], v82, s59, v[114:115]
	v_lshl_add_u64 v[82:83], v[82:83], 0, v[116:117]
	global_store_dwordx4 v[82:83], v[90:93], off
	v_pk_mul_f32 v[230:231], v[78:79], s[98:99]
	v_exp_f32_e32 v230, v230
	v_exp_f32_e32 v231, v231
	v_add_f32_e32 v230, 1.0, v230
	v_add_f32_e32 v231, 1.0, v231
	v_rcp_f32_e32 v230, v230
	v_rcp_f32_e32 v231, v231
	v_mul_f32_e32 v234, v78, v230
	v_mul_f32_e32 v235, v79, v231
	v_pk_mul_f32 v[234:235], v[234:235], v[74:75]
	v_cvt_pk_bf16_f32 v74, v234, v235
	v_pk_mul_f32 v[230:231], v[80:81], s[98:99]
	v_exp_f32_e32 v230, v230
	v_exp_f32_e32 v231, v231
	v_add_f32_e32 v230, 1.0, v230
	v_add_f32_e32 v231, 1.0, v231
	v_rcp_f32_e32 v230, v230
	v_rcp_f32_e32 v231, v231
	v_mul_f32_e32 v236, v80, v230
	v_mul_f32_e32 v237, v81, v231
	v_pk_mul_f32 v[236:237], v[236:237], v[76:77]
	v_cvt_pk_bf16_f32 v75, v236, v237
	v_pk_mul_f32 v[230:231], v[70:71], s[98:99]
	v_exp_f32_e32 v230, v230
	v_exp_f32_e32 v231, v231
	v_add_f32_e32 v230, 1.0, v230
	v_add_f32_e32 v231, 1.0, v231
	v_rcp_f32_e32 v230, v230
	v_rcp_f32_e32 v231, v231
	v_mul_f32_e32 v238, v70, v230
	v_mul_f32_e32 v239, v71, v231
	v_pk_mul_f32 v[238:239], v[238:239], v[66:67]
	v_cvt_pk_bf16_f32 v76, v238, v239
	v_pk_mul_f32 v[230:231], v[72:73], s[98:99]
	v_exp_f32_e32 v230, v230
	v_exp_f32_e32 v231, v231
	v_add_f32_e32 v230, 1.0, v230
	v_add_f32_e32 v231, 1.0, v231
	v_rcp_f32_e32 v230, v230
	v_rcp_f32_e32 v231, v231
	v_mul_f32_e32 v240, v72, v230
	v_mul_f32_e32 v241, v73, v231
	v_pk_mul_f32 v[240:241], v[240:241], v[68:69]
	v_cvt_pk_bf16_f32 v77, v240, v241
	v_or_b32_e32 v66, 48, v148
	v_mad_i64_i32 v[66:67], s[42:43], v66, s59, v[114:115]
	v_lshl_add_u64 v[66:67], v[66:67], 0, v[116:117]
	global_store_dwordx4 v[66:67], v[74:77], off
	v_pk_mul_f32 v[230:231], v[62:63], s[98:99]
	v_exp_f32_e32 v230, v230
	v_exp_f32_e32 v231, v231
	v_add_f32_e32 v230, 1.0, v230
	v_add_f32_e32 v231, 1.0, v231
	v_rcp_f32_e32 v230, v230
	v_rcp_f32_e32 v231, v231
	v_mul_f32_e32 v234, v62, v230
	v_mul_f32_e32 v235, v63, v231
	v_pk_mul_f32 v[234:235], v[234:235], v[58:59]
	v_cvt_pk_bf16_f32 v58, v234, v235
	v_pk_mul_f32 v[230:231], v[64:65], s[98:99]
	v_exp_f32_e32 v230, v230
	v_exp_f32_e32 v231, v231
	v_add_f32_e32 v230, 1.0, v230
	v_add_f32_e32 v231, 1.0, v231
	v_rcp_f32_e32 v230, v230
	v_rcp_f32_e32 v231, v231
	v_mul_f32_e32 v236, v64, v230
	v_mul_f32_e32 v237, v65, v231
	v_pk_mul_f32 v[236:237], v[236:237], v[60:61]
	v_cvt_pk_bf16_f32 v59, v236, v237
	v_pk_mul_f32 v[230:231], v[54:55], s[98:99]
	v_exp_f32_e32 v230, v230
	v_exp_f32_e32 v231, v231
	v_add_f32_e32 v230, 1.0, v230
	v_add_f32_e32 v231, 1.0, v231
	v_rcp_f32_e32 v230, v230
	v_rcp_f32_e32 v231, v231
	v_mul_f32_e32 v238, v54, v230
	v_mul_f32_e32 v239, v55, v231
	v_pk_mul_f32 v[238:239], v[238:239], v[50:51]
	v_cvt_pk_bf16_f32 v60, v238, v239
	v_pk_mul_f32 v[230:231], v[56:57], s[98:99]
	v_exp_f32_e32 v230, v230
	v_exp_f32_e32 v231, v231
	v_add_f32_e32 v230, 1.0, v230
	v_add_f32_e32 v231, 1.0, v231
	v_rcp_f32_e32 v230, v230
	v_rcp_f32_e32 v231, v231
	v_mul_f32_e32 v240, v56, v230
	v_mul_f32_e32 v241, v57, v231
	v_pk_mul_f32 v[240:241], v[240:241], v[52:53]
	v_add_u32_e32 v66, 0x80, v148
	v_cvt_pk_bf16_f32 v61, v240, v241
	v_mad_i64_i32 v[50:51], s[42:43], v66, s59, v[114:115]
	v_lshl_add_u64 v[50:51], v[50:51], 0, v[116:117]
	global_store_dwordx4 v[50:51], v[58:61], off
	v_pk_mul_f32 v[230:231], v[46:47], s[98:99]
	v_exp_f32_e32 v230, v230
	v_exp_f32_e32 v231, v231
	v_add_f32_e32 v230, 1.0, v230
	v_add_f32_e32 v231, 1.0, v231
	v_rcp_f32_e32 v230, v230
	v_rcp_f32_e32 v231, v231
	v_mul_f32_e32 v234, v46, v230
	v_mul_f32_e32 v235, v47, v231
	v_pk_mul_f32 v[234:235], v[234:235], v[42:43]
	v_cvt_pk_bf16_f32 v42, v234, v235
	v_pk_mul_f32 v[230:231], v[48:49], s[98:99]
	v_exp_f32_e32 v230, v230
	v_exp_f32_e32 v231, v231
	v_add_f32_e32 v230, 1.0, v230
	v_add_f32_e32 v231, 1.0, v231
	v_rcp_f32_e32 v230, v230
	v_rcp_f32_e32 v231, v231
	v_mul_f32_e32 v236, v48, v230
	v_mul_f32_e32 v237, v49, v231
	v_pk_mul_f32 v[236:237], v[236:237], v[44:45]
	v_cvt_pk_bf16_f32 v43, v236, v237
	v_pk_mul_f32 v[230:231], v[38:39], s[98:99]
	v_exp_f32_e32 v230, v230
	v_exp_f32_e32 v231, v231
	v_add_f32_e32 v230, 1.0, v230
	v_add_f32_e32 v231, 1.0, v231
	v_rcp_f32_e32 v230, v230
	v_rcp_f32_e32 v231, v231
	v_mul_f32_e32 v238, v38, v230
	v_mul_f32_e32 v239, v39, v231
	v_pk_mul_f32 v[238:239], v[238:239], v[34:35]
	v_cvt_pk_bf16_f32 v44, v238, v239
	v_pk_mul_f32 v[230:231], v[40:41], s[98:99]
	v_exp_f32_e32 v230, v230
	v_exp_f32_e32 v231, v231
	v_add_f32_e32 v230, 1.0, v230
	v_add_f32_e32 v231, 1.0, v231
	v_rcp_f32_e32 v230, v230
	v_rcp_f32_e32 v231, v231
	v_mul_f32_e32 v240, v40, v230
	v_mul_f32_e32 v241, v41, v231
	v_pk_mul_f32 v[240:241], v[240:241], v[36:37]
	v_cvt_pk_bf16_f32 v45, v240, v241
	v_add_u32_e32 v34, 0x90, v148
	v_mad_i64_i32 v[34:35], s[42:43], v34, s59, v[114:115]
	v_lshl_add_u64 v[34:35], v[34:35], 0, v[116:117]
	global_store_dwordx4 v[34:35], v[42:45], off
	v_pk_mul_f32 v[230:231], v[30:31], s[98:99]
	v_exp_f32_e32 v230, v230
	v_exp_f32_e32 v231, v231
	v_add_f32_e32 v230, 1.0, v230
	v_add_f32_e32 v231, 1.0, v231
	v_rcp_f32_e32 v230, v230
	v_rcp_f32_e32 v231, v231
	v_mul_f32_e32 v234, v30, v230
	v_mul_f32_e32 v235, v31, v231
	v_pk_mul_f32 v[234:235], v[234:235], v[26:27]
	v_cvt_pk_bf16_f32 v26, v234, v235
	v_pk_mul_f32 v[230:231], v[32:33], s[98:99]
	v_exp_f32_e32 v230, v230
	v_exp_f32_e32 v231, v231
	v_add_f32_e32 v230, 1.0, v230
	v_add_f32_e32 v231, 1.0, v231
	v_rcp_f32_e32 v230, v230
	v_rcp_f32_e32 v231, v231
	v_mul_f32_e32 v236, v32, v230
	v_mul_f32_e32 v237, v33, v231
	v_pk_mul_f32 v[236:237], v[236:237], v[28:29]
	v_cvt_pk_bf16_f32 v27, v236, v237
	v_pk_mul_f32 v[230:231], v[22:23], s[98:99]
	v_exp_f32_e32 v230, v230
	v_exp_f32_e32 v231, v231
	v_add_f32_e32 v230, 1.0, v230
	v_add_f32_e32 v231, 1.0, v231
	v_rcp_f32_e32 v230, v230
	v_rcp_f32_e32 v231, v231
	v_mul_f32_e32 v238, v22, v230
	v_mul_f32_e32 v239, v23, v231
	v_pk_mul_f32 v[238:239], v[238:239], v[18:19]
	v_cvt_pk_bf16_f32 v28, v238, v239
	v_pk_mul_f32 v[230:231], v[24:25], s[98:99]
	v_exp_f32_e32 v230, v230
	v_exp_f32_e32 v231, v231
	v_add_f32_e32 v230, 1.0, v230
	v_add_f32_e32 v231, 1.0, v231
	v_rcp_f32_e32 v230, v230
	v_rcp_f32_e32 v231, v231
	v_mul_f32_e32 v240, v24, v230
	v_mul_f32_e32 v241, v25, v231
	v_pk_mul_f32 v[240:241], v[240:241], v[20:21]
	v_cvt_pk_bf16_f32 v29, v240, v241
	v_add_u32_e32 v18, 0xa0, v148
	v_mad_i64_i32 v[18:19], s[42:43], v18, s59, v[114:115]
	v_lshl_add_u64 v[18:19], v[18:19], 0, v[116:117]
	global_store_dwordx4 v[18:19], v[26:29], off
	v_pk_mul_f32 v[230:231], v[14:15], s[98:99]
	v_exp_f32_e32 v230, v230
	v_exp_f32_e32 v231, v231
	v_add_f32_e32 v230, 1.0, v230
	v_add_f32_e32 v231, 1.0, v231
	v_rcp_f32_e32 v230, v230
	v_rcp_f32_e32 v231, v231
	v_mul_f32_e32 v234, v14, v230
	v_mul_f32_e32 v235, v15, v231
	v_pk_mul_f32 v[234:235], v[234:235], v[10:11]
	v_cvt_pk_bf16_f32 v10, v234, v235
	v_pk_mul_f32 v[230:231], v[16:17], s[98:99]
	v_exp_f32_e32 v230, v230
	v_exp_f32_e32 v231, v231
	v_add_f32_e32 v230, 1.0, v230
	v_add_f32_e32 v231, 1.0, v231
	v_rcp_f32_e32 v230, v230
	v_rcp_f32_e32 v231, v231
	v_mul_f32_e32 v236, v16, v230
	v_mul_f32_e32 v237, v17, v231
	v_pk_mul_f32 v[236:237], v[236:237], v[12:13]
	v_cvt_pk_bf16_f32 v11, v236, v237
	v_pk_mul_f32 v[230:231], v[6:7], s[98:99]
	v_exp_f32_e32 v230, v230
	v_exp_f32_e32 v231, v231
	v_add_f32_e32 v230, 1.0, v230
	v_add_f32_e32 v231, 1.0, v231
	v_rcp_f32_e32 v230, v230
	v_rcp_f32_e32 v231, v231
	v_mul_f32_e32 v238, v6, v230
	v_mul_f32_e32 v239, v7, v231
	v_pk_mul_f32 v[238:239], v[238:239], v[2:3]
	v_cvt_pk_bf16_f32 v12, v238, v239
	v_pk_mul_f32 v[230:231], v[8:9], s[98:99]
	v_exp_f32_e32 v230, v230
	v_exp_f32_e32 v231, v231
	v_add_f32_e32 v230, 1.0, v230
	v_add_f32_e32 v231, 1.0, v231
	v_rcp_f32_e32 v230, v230
	v_rcp_f32_e32 v231, v231
	v_mul_f32_e32 v240, v8, v230
	v_mul_f32_e32 v241, v9, v231
	v_pk_mul_f32 v[240:241], v[240:241], v[4:5]
	v_cvt_pk_bf16_f32 v13, v240, v241
	v_add_u32_e32 v2, 0xb0, v148
	v_mad_i64_i32 v[2:3], s[42:43], v2, s59, v[114:115]
	v_lshl_add_u64 v[2:3], v[2:3], 0, v[116:117]
	s_mov_b64 s[42:43], -1
	s_and_b64 vcc, exec, s[38:39]
	global_store_dwordx4 v[2:3], v[10:13], off
	s_cbranch_vccz .LBB0_5811
	s_andn2_b64 vcc, exec, s[6:7]
	s_cbranch_vccnz .LBB0_5810
	s_nop 0
	s_branch .LBB0_5810
